# GEMM ping-pong hand-off: s_setprio 1 raised before the barrier, duplicate lgkmcnt(0) after it dropped, s_setprio 0 lowered after the end barrier (24 segments)
# speedup vs baseline: 1.0246x; 1.0246x over previous
; #define PG8_STAGE(bufoff, gbase, voff) do { _Pragma("unroll") for (int _i = 0; _i < 2; ++_i) \
;         __builtin_amdgcn_global_load_lds((const unsigned*)((const char*)(gbase) + (voff)[_i]), (PG8_LAS unsigned*)(lds + (bufoff) + ldsw + _i * 8192), 16, 0, 0); } while (0)
; #define PG8_LDA(dst, b, h) do { _Pragma("unroll") for (int m = 0; m < 4; ++m) _Pragma("unroll") for (int k = 0; k < 2; ++k) dst[m][k] = *(const PG8_LAS bf16x8*)(lds + PG8_SA(b, h) + aoff + m * 2048 + k * 1024); } while (0)
; #define PG8_LDB(dst, b, h) do { _Pragma("unroll") for (int n = 0; n < 2; ++n) _Pragma("unroll") for (int k = 0; k < 2; ++k) dst[n][k] = *(const PG8_LAS bf16x8*)(lds + PG8_SB(b, h) + boff + n * 2048 + k * 1024); } while (0)
; #define PG8_MMA(ai, bj, At, Bt) do { __builtin_amdgcn_s_setprio(1); _Pragma("unroll") for (int m = 0; m < 4; ++m) _Pragma("unroll") for (int n = 0; n < 2; ++n) _Pragma("unroll") for (int k = 0; k < 2; ++k) \
;         acc[ai][bj][m][n] = __builtin_amdgcn_mfma_f32_16x16x32_bf16(Bt[n][k], At[m][k], acc[ai][bj][m][n], 0, 0, 0); __builtin_amdgcn_s_setprio(0); } while (0)
; #define PG8_WAIT_V(n) asm volatile("s_waitcnt vmcnt(" #n ")" ::: "memory")
; #define PG8_WAIT_L(n) asm volatile("s_waitcnt lgkmcnt(" #n ")" ::: "memory")
; template <class Epi, class Sched, bool ALIGN_EPI = false, bool SP2 = false>
; __device__ __forceinline__ void gemm_phase(PG8_LAS unsigned char* lds, const Gemm g, const Sched& S, const Epi& E) {
;     ...
;             const bool last = (t == nt - 2);
;             const char* a1 = cA + (size_t)(t + 1) * kstep;
;             const char* a2 = last ? nA : cA + (size_t)(t + 2) * kstep; const char* b2 = last ? nB : cB + (size_t)(t + 2) * kstep;
;             const char* a3 = a2 + kstep; const char* b3 = b2 + kstep;
;             if (last && has_next) S.a_ready(nxt);
;             if constexpr (SP2) {
;             PG8_LDB(B0, 0, 0); PG8_LDB(B1, 0, 1); PG8_SCHED; PG8_LDA(At, 0, 0); PG8_STAGE(PG8_SA(1, 1), a1 + hstep, voffA);
;             PG8_WAIT_V(8); PG8_WAIT_L(0); PG8_BAR; PG8_MMA(0, 0, At, B0); PG8_MMA(0, 1, At, B1); PG8_BAR; PG8_SCHED;
;             PG8_LDA(At, 0, 1); PG8_STAGE(PG8_SB(0, 0), b2, voffB); PG8_STAGE(PG8_SB(0, 1), b2 + hstep, voffB); PG8_STAGE(PG8_SA(0, 0), a2, voffA);
;             PG8_WAIT_V(8); PG8_WAIT_L(0); PG8_BAR; PG8_MMA(1, 0, At, B0); PG8_MMA(1, 1, At, B1); PG8_BAR; PG8_SCHED;
.LBB0_146:
	s_add_u32 s44, s24, 0xfff80080
	s_addc_u32 s45, s25, -1
	s_add_i32 s55, 0, 0x10000
	s_cmp_eq_u32 s54, 28
	s_cselect_b32 s47, s21, s45
	s_cselect_b32 s46, s48, s44
	v_add_u32_e32 v167, s55, v147
	s_cselect_b32 s45, s19, s51
	s_cselect_b32 s44, s49, s50
	s_add_i32 s62, 0, 0x14000
	ds_read_b128 v[142:145], v167
	ds_read_b128 v[168:171], v167 offset:1024
	ds_read_b128 v[172:175], v167 offset:2048
	ds_read_b128 v[176:179], v167 offset:3072
	v_add_u32_e32 v167, s62, v147
	ds_read_b128 v[180:183], v167
	ds_read_b128 v[184:187], v167 offset:1024
	ds_read_b128 v[188:191], v167 offset:2048
	ds_read_b128 v[204:207], v167 offset:3072
	v_lshl_add_u64 v[192:193], s[24:25], 0, v[138:139]
	s_add_i32 m0, s1, 0xc000
	ds_read_b128 v[216:219], v166
	ds_read_b128 v[220:223], v166 offset:1024
	ds_read_b128 v[224:227], v166 offset:2048
	ds_read_b128 v[228:231], v166 offset:3072
	ds_read_b128 v[232:235], v166 offset:4096
	ds_read_b128 v[236:239], v166 offset:5120
	ds_read_b128 v[240:243], v166 offset:6144
	ds_read_b128 v[244:247], v166 offset:7168
	global_load_lds_dwordx4 v[192:193], off
	v_lshl_add_u64 v[192:193], s[24:25], 0, v[140:141]
	s_add_i32 m0, s1, 0xe000
	s_nop 0
	global_load_lds_dwordx4 v[192:193], off
	s_waitcnt vmcnt(8)
	s_waitcnt lgkmcnt(0)
	s_setprio 1
	s_barrier
	v_mfma_f32_16x16x32_bf16 v[126:129], v[142:145], v[216:219], v[126:129]
	v_mfma_f32_16x16x32_bf16 v[122:125], v[172:175], v[216:219], v[122:125]
	v_mfma_f32_16x16x32_bf16 v[114:117], v[142:145], v[224:227], v[114:117]
	v_mfma_f32_16x16x32_bf16 v[106:109], v[172:175], v[224:227], v[106:109]
	v_mfma_f32_16x16x32_bf16 v[98:101], v[142:145], v[232:235], v[98:101]
	v_mfma_f32_16x16x32_bf16 v[90:93], v[172:175], v[232:235], v[90:93]
	v_mfma_f32_16x16x32_bf16 v[82:85], v[142:145], v[240:243], v[82:85]
	v_mfma_f32_16x16x32_bf16 v[74:77], v[172:175], v[240:243], v[74:77]
	v_mfma_f32_16x16x32_bf16 v[126:129], v[168:171], v[220:223], v[126:129]
	v_mfma_f32_16x16x32_bf16 v[122:125], v[176:179], v[220:223], v[122:125]
	v_mfma_f32_16x16x32_bf16 v[114:117], v[168:171], v[228:231], v[114:117]
	v_mfma_f32_16x16x32_bf16 v[106:109], v[176:179], v[228:231], v[106:109]
	v_mfma_f32_16x16x32_bf16 v[98:101], v[168:171], v[236:239], v[98:101]
	v_mfma_f32_16x16x32_bf16 v[90:93], v[176:179], v[236:239], v[90:93]
	v_mfma_f32_16x16x32_bf16 v[82:85], v[168:171], v[244:247], v[82:85]
	v_mfma_f32_16x16x32_bf16 v[74:77], v[176:179], v[244:247], v[74:77]
	s_setprio 0
	s_setprio 1
	v_mfma_f32_16x16x32_bf16 v[118:121], v[180:183], v[216:219], v[118:121]
	v_mfma_f32_16x16x32_bf16 v[110:113], v[188:191], v[216:219], v[110:113]
	v_mfma_f32_16x16x32_bf16 v[102:105], v[180:183], v[224:227], v[102:105]
	v_mfma_f32_16x16x32_bf16 v[94:97], v[188:191], v[224:227], v[94:97]
	v_mfma_f32_16x16x32_bf16 v[86:89], v[180:183], v[232:235], v[86:89]
	v_mfma_f32_16x16x32_bf16 v[78:81], v[188:191], v[232:235], v[78:81]
	v_mfma_f32_16x16x32_bf16 v[70:73], v[180:183], v[240:243], v[70:73]
	v_mfma_f32_16x16x32_bf16 v[66:69], v[188:191], v[240:243], v[66:69]
	v_mfma_f32_16x16x32_bf16 v[118:121], v[184:187], v[220:223], v[118:121]
	v_mfma_f32_16x16x32_bf16 v[110:113], v[204:207], v[220:223], v[110:113]
	v_mfma_f32_16x16x32_bf16 v[102:105], v[184:187], v[228:231], v[102:105]
	v_mfma_f32_16x16x32_bf16 v[94:97], v[204:207], v[228:231], v[94:97]
	v_mfma_f32_16x16x32_bf16 v[86:89], v[184:187], v[236:239], v[86:89]
	v_mfma_f32_16x16x32_bf16 v[78:81], v[204:207], v[236:239], v[78:81]
	v_mfma_f32_16x16x32_bf16 v[70:73], v[184:187], v[244:247], v[70:73]
	v_mfma_f32_16x16x32_bf16 v[66:69], v[204:207], v[244:247], v[66:69]
	s_barrier
	s_setprio 0
	s_add_i32 s55, s55, s0
	v_lshl_add_u64 v[192:193], s[44:45], 0, v[0:1]
	s_mov_b32 m0, s55
	ds_read_b128 v[216:219], v166 offset:16384
	ds_read_b128 v[220:223], v166 offset:17408
	ds_read_b128 v[224:227], v166 offset:18432
	ds_read_b128 v[228:231], v166 offset:19456
	ds_read_b128 v[232:235], v166 offset:20480
	ds_read_b128 v[236:239], v166 offset:21504
	ds_read_b128 v[240:243], v166 offset:22528
	ds_read_b128 v[244:247], v166 offset:23552
	global_load_lds_dwordx4 v[192:193], off
	s_add_i32 m0, s55, 0x2000
	s_add_u32 s58, s44, 0x80000
	v_lshl_add_u64 v[248:249], s[44:45], 0, v[130:131]
	s_addc_u32 s59, s45, 0
	s_add_i32 s55, s62, s0
	global_load_lds_dwordx4 v[248:249], off
	v_lshl_add_u64 v[250:251], s[58:59], 0, v[0:1]
	s_mov_b32 m0, s55
	v_lshl_add_u64 v[200:201], s[46:47], 0, v[132:133]
	global_load_lds_dwordx4 v[250:251], off
	v_lshl_add_u64 v[250:251], s[58:59], 0, v[130:131]
	s_add_i32 m0, s55, 0x2000
	s_nop 0
	global_load_lds_dwordx4 v[250:251], off
	v_lshl_add_u64 v[250:251], s[46:47], 0, v[134:135]
	s_mov_b32 m0, s1
	s_nop 0
	global_load_lds_dwordx4 v[250:251], off
	s_mov_b32 m0, s2
	s_nop 0
	global_load_lds_dwordx4 v[200:201], off
	s_waitcnt vmcnt(8)
	s_waitcnt lgkmcnt(0)
	s_setprio 1
	s_barrier
; #define PG8_STAGE(bufoff, gbase, voff) do { _Pragma("unroll") for (int _i = 0; _i < 2; ++_i) \
;         __builtin_amdgcn_global_load_lds((const unsigned*)((const char*)(gbase) + (voff)[_i]), (PG8_LAS unsigned*)(lds + (bufoff) + ldsw + _i * 8192), 16, 0, 0); } while (0)
; #define PG8_LDA(dst, b, h) do { _Pragma("unroll") for (int m = 0; m < 4; ++m) _Pragma("unroll") for (int k = 0; k < 2; ++k) dst[m][k] = *(const PG8_LAS bf16x8*)(lds + PG8_SA(b, h) + aoff + m * 2048 + k * 1024); } while (0)
; #define PG8_LDB(dst, b, h) do { _Pragma("unroll") for (int n = 0; n < 2; ++n) _Pragma("unroll") for (int k = 0; k < 2; ++k) dst[n][k] = *(const PG8_LAS bf16x8*)(lds + PG8_SB(b, h) + boff + n * 2048 + k * 1024); } while (0)
; #define PG8_MMA(ai, bj, At, Bt) do { __builtin_amdgcn_s_setprio(1); _Pragma("unroll") for (int m = 0; m < 4; ++m) _Pragma("unroll") for (int n = 0; n < 2; ++n) _Pragma("unroll") for (int k = 0; k < 2; ++k) \
;         acc[ai][bj][m][n] = __builtin_amdgcn_mfma_f32_16x16x32_bf16(Bt[n][k], At[m][k], acc[ai][bj][m][n], 0, 0, 0); __builtin_amdgcn_s_setprio(0); } while (0)
; #define PG8_WAIT_V(n) asm volatile("s_waitcnt vmcnt(" #n ")" ::: "memory")
; #define PG8_WAIT_L(n) asm volatile("s_waitcnt lgkmcnt(" #n ")" ::: "memory")
; #define PG8_BAR __builtin_amdgcn_s_barrier()
; #define PG8_SCHED __builtin_amdgcn_sched_barrier(0)
; template <class Epi, class Sched, bool ALIGN_EPI = false, bool SP2 = false>
; __device__ __forceinline__ void gemm_phase(PG8_LAS unsigned char* lds, const Gemm g, const Sched& S, const Epi& E) {
;     ...
;             PG8_WAIT_V(8); PG8_WAIT_L(0); PG8_BAR; PG8_MMA(1, 0, At, B0); PG8_MMA(1, 1, At, B1); PG8_BAR; PG8_SCHED;
;             PG8_LDB(B0, 1, 0); PG8_LDB(B1, 1, 1); PG8_SCHED; PG8_LDA(At, 1, 0); PG8_STAGE(PG8_SA(0, 1), a2 + hstep, voffA);
;             PG8_WAIT_V(8); PG8_WAIT_L(0); PG8_BAR; PG8_MMA(0, 0, At, B0); PG8_MMA(0, 1, At, B1); PG8_BAR; PG8_SCHED;
	v_mfma_f32_16x16x32_bf16 v[62:65], v[142:145], v[216:219], v[62:65]
	v_mfma_f32_16x16x32_bf16 v[58:61], v[172:175], v[216:219], v[58:61]
	v_mfma_f32_16x16x32_bf16 v[50:53], v[142:145], v[224:227], v[50:53]
	v_mfma_f32_16x16x32_bf16 v[42:45], v[172:175], v[224:227], v[42:45]
	v_mfma_f32_16x16x32_bf16 v[34:37], v[142:145], v[232:235], v[34:37]
	v_mfma_f32_16x16x32_bf16 v[26:29], v[172:175], v[232:235], v[26:29]
	v_mfma_f32_16x16x32_bf16 v[18:21], v[142:145], v[240:243], v[18:21]
	v_mfma_f32_16x16x32_bf16 v[10:13], v[172:175], v[240:243], v[10:13]
	v_mfma_f32_16x16x32_bf16 v[62:65], v[168:171], v[220:223], v[62:65]
	v_mfma_f32_16x16x32_bf16 v[58:61], v[176:179], v[220:223], v[58:61]
	v_mfma_f32_16x16x32_bf16 v[50:53], v[168:171], v[228:231], v[50:53]
	v_mfma_f32_16x16x32_bf16 v[42:45], v[176:179], v[228:231], v[42:45]
	v_mfma_f32_16x16x32_bf16 v[34:37], v[168:171], v[236:239], v[34:37]
	v_mfma_f32_16x16x32_bf16 v[26:29], v[176:179], v[236:239], v[26:29]
	v_mfma_f32_16x16x32_bf16 v[18:21], v[168:171], v[244:247], v[18:21]
	v_mfma_f32_16x16x32_bf16 v[10:13], v[176:179], v[244:247], v[10:13]
	s_setprio 0
	s_setprio 1
	v_mfma_f32_16x16x32_bf16 v[54:57], v[180:183], v[216:219], v[54:57]
	v_mfma_f32_16x16x32_bf16 v[46:49], v[188:191], v[216:219], v[46:49]
	v_mfma_f32_16x16x32_bf16 v[38:41], v[180:183], v[224:227], v[38:41]
	v_mfma_f32_16x16x32_bf16 v[30:33], v[188:191], v[224:227], v[30:33]
	v_mfma_f32_16x16x32_bf16 v[22:25], v[180:183], v[232:235], v[22:25]
	v_mfma_f32_16x16x32_bf16 v[14:17], v[188:191], v[232:235], v[14:17]
	v_mfma_f32_16x16x32_bf16 v[6:9], v[180:183], v[240:243], v[6:9]
	v_mfma_f32_16x16x32_bf16 v[2:5], v[188:191], v[240:243], v[2:5]
	v_mfma_f32_16x16x32_bf16 v[54:57], v[184:187], v[220:223], v[54:57]
	v_mfma_f32_16x16x32_bf16 v[46:49], v[204:207], v[220:223], v[46:49]
	v_mfma_f32_16x16x32_bf16 v[38:41], v[184:187], v[228:231], v[38:41]
	v_mfma_f32_16x16x32_bf16 v[30:33], v[204:207], v[228:231], v[30:33]
	v_mfma_f32_16x16x32_bf16 v[22:25], v[184:187], v[236:239], v[22:25]
	v_mfma_f32_16x16x32_bf16 v[14:17], v[204:207], v[236:239], v[14:17]
	v_mfma_f32_16x16x32_bf16 v[6:9], v[184:187], v[244:247], v[6:9]
	v_mfma_f32_16x16x32_bf16 v[2:5], v[204:207], v[244:247], v[2:5]
	s_barrier
	s_setprio 0
	s_add_i32 s55, 0, 0x18000
	v_add_u32_e32 v167, s55, v147
	s_add_i32 s58, 0, 0x1c000
	ds_read_b128 v[142:145], v167
	ds_read_b128 v[168:171], v167 offset:1024
	ds_read_b128 v[172:175], v167 offset:2048
	ds_read_b128 v[176:179], v167 offset:3072
	v_add_u32_e32 v167, s58, v147
	ds_read_b128 v[180:183], v167
	ds_read_b128 v[184:187], v167 offset:1024
	ds_read_b128 v[188:191], v167 offset:2048
	ds_read_b128 v[204:207], v167 offset:3072
	s_add_u32 s46, s46, 0x80000
	s_addc_u32 s47, s47, 0
	s_mov_b32 m0, s3
	v_lshl_add_u64 v[202:203], s[46:47], 0, v[134:135]
	ds_read_b128 v[216:219], v166 offset:32768
	ds_read_b128 v[220:223], v166 offset:33792
	ds_read_b128 v[224:227], v166 offset:34816
	ds_read_b128 v[228:231], v166 offset:35840
	ds_read_b128 v[232:235], v166 offset:36864
	ds_read_b128 v[236:239], v166 offset:37888
	ds_read_b128 v[240:243], v166 offset:38912
	ds_read_b128 v[244:247], v166 offset:39936
	global_load_lds_dwordx4 v[202:203], off
	v_lshl_add_u64 v[202:203], s[46:47], 0, v[132:133]
	s_mov_b32 m0, s10
	s_nop 0
	global_load_lds_dwordx4 v[202:203], off
	s_waitcnt vmcnt(8)
	s_waitcnt lgkmcnt(0)
	s_setprio 1
	s_barrier
	v_mfma_f32_16x16x32_bf16 v[126:129], v[142:145], v[216:219], v[126:129]
	v_mfma_f32_16x16x32_bf16 v[122:125], v[172:175], v[216:219], v[122:125]
	v_mfma_f32_16x16x32_bf16 v[114:117], v[142:145], v[224:227], v[114:117]
	v_mfma_f32_16x16x32_bf16 v[106:109], v[172:175], v[224:227], v[106:109]
	v_mfma_f32_16x16x32_bf16 v[98:101], v[142:145], v[232:235], v[98:101]
	v_mfma_f32_16x16x32_bf16 v[90:93], v[172:175], v[232:235], v[90:93]
	v_mfma_f32_16x16x32_bf16 v[82:85], v[142:145], v[240:243], v[82:85]
	v_mfma_f32_16x16x32_bf16 v[74:77], v[172:175], v[240:243], v[74:77]
	v_mfma_f32_16x16x32_bf16 v[126:129], v[168:171], v[220:223], v[126:129]
	v_mfma_f32_16x16x32_bf16 v[122:125], v[176:179], v[220:223], v[122:125]
	v_mfma_f32_16x16x32_bf16 v[114:117], v[168:171], v[228:231], v[114:117]
	v_mfma_f32_16x16x32_bf16 v[106:109], v[176:179], v[228:231], v[106:109]
	v_mfma_f32_16x16x32_bf16 v[98:101], v[168:171], v[236:239], v[98:101]
	v_mfma_f32_16x16x32_bf16 v[90:93], v[176:179], v[236:239], v[90:93]
	v_mfma_f32_16x16x32_bf16 v[82:85], v[168:171], v[244:247], v[82:85]
	v_mfma_f32_16x16x32_bf16 v[74:77], v[176:179], v[244:247], v[74:77]
	s_setprio 0
	s_setprio 1
	v_mfma_f32_16x16x32_bf16 v[118:121], v[180:183], v[216:219], v[118:121]
	v_mfma_f32_16x16x32_bf16 v[110:113], v[188:191], v[216:219], v[110:113]
	v_mfma_f32_16x16x32_bf16 v[102:105], v[180:183], v[224:227], v[102:105]
	v_mfma_f32_16x16x32_bf16 v[94:97], v[188:191], v[224:227], v[94:97]
	v_mfma_f32_16x16x32_bf16 v[86:89], v[180:183], v[232:235], v[86:89]
	v_mfma_f32_16x16x32_bf16 v[78:81], v[188:191], v[232:235], v[78:81]
	v_mfma_f32_16x16x32_bf16 v[70:73], v[180:183], v[240:243], v[70:73]
	v_mfma_f32_16x16x32_bf16 v[66:69], v[188:191], v[240:243], v[66:69]
	v_mfma_f32_16x16x32_bf16 v[118:121], v[184:187], v[220:223], v[118:121]
	v_mfma_f32_16x16x32_bf16 v[110:113], v[204:207], v[220:223], v[110:113]
	v_mfma_f32_16x16x32_bf16 v[102:105], v[184:187], v[228:231], v[102:105]
	v_mfma_f32_16x16x32_bf16 v[94:97], v[204:207], v[228:231], v[94:97]
	v_mfma_f32_16x16x32_bf16 v[86:89], v[184:187], v[236:239], v[86:89]
	v_mfma_f32_16x16x32_bf16 v[78:81], v[204:207], v[236:239], v[78:81]
	v_mfma_f32_16x16x32_bf16 v[70:73], v[184:187], v[244:247], v[70:73]
	v_mfma_f32_16x16x32_bf16 v[66:69], v[204:207], v[244:247], v[66:69]
	s_barrier
; #define PG8_STAGE(bufoff, gbase, voff) do { _Pragma("unroll") for (int _i = 0; _i < 2; ++_i) \
;         __builtin_amdgcn_global_load_lds((const unsigned*)((const char*)(gbase) + (voff)[_i]), (PG8_LAS unsigned*)(lds + (bufoff) + ldsw + _i * 8192), 16, 0, 0); } while (0)
; #define PG8_LDA(dst, b, h) do { _Pragma("unroll") for (int m = 0; m < 4; ++m) _Pragma("unroll") for (int k = 0; k < 2; ++k) dst[m][k] = *(const PG8_LAS bf16x8*)(lds + PG8_SA(b, h) + aoff + m * 2048 + k * 1024); } while (0)
; #define PG8_MMA(ai, bj, At, Bt) do { __builtin_amdgcn_s_setprio(1); _Pragma("unroll") for (int m = 0; m < 4; ++m) _Pragma("unroll") for (int n = 0; n < 2; ++n) _Pragma("unroll") for (int k = 0; k < 2; ++k) \
;         acc[ai][bj][m][n] = __builtin_amdgcn_mfma_f32_16x16x32_bf16(Bt[n][k], At[m][k], acc[ai][bj][m][n], 0, 0, 0); __builtin_amdgcn_s_setprio(0); } while (0)
; #define PG8_WAIT_V(n) asm volatile("s_waitcnt vmcnt(" #n ")" ::: "memory")
; #define PG8_WAIT_L(n) asm volatile("s_waitcnt lgkmcnt(" #n ")" ::: "memory")
; #define PG8_BAR __builtin_amdgcn_s_barrier()
; #define PG8_SCHED __builtin_amdgcn_sched_barrier(0)
; template <class Epi, class Sched, bool ALIGN_EPI = false, bool SP2 = false>
; __device__ __forceinline__ void gemm_phase(PG8_LAS unsigned char* lds, const Gemm g, const Sched& S, const Epi& E) {
;     ...
;         for (int t = 0; t < nt; t += 2) {
;             const bool last = (t == nt - 2);
;             const char* a1 = cA + (size_t)(t + 1) * kstep;
;             const char* a2 = last ? nA : cA + (size_t)(t + 2) * kstep; const char* b2 = last ? nB : cB + (size_t)(t + 2) * kstep;
;     ...
;             PG8_LDA(At, 1, 1); PG8_STAGE(PG8_SB(1, 0), b3, voffB); PG8_STAGE(PG8_SB(1, 1), b3 + hstep, voffB); PG8_STAGE(PG8_SA(1, 0), a3, voffA);
;             PG8_WAIT_V(8); PG8_WAIT_L(0); PG8_BAR; PG8_MMA(1, 0, At, B0); PG8_MMA(1, 1, At, B1); PG8_BAR; PG8_SCHED;
	s_setprio 0
	s_add_i32 s46, s55, s0
	v_lshl_add_u64 v[192:193], v[192:193], 0, s[56:57]
	s_mov_b32 m0, s46
	ds_read_b128 v[216:219], v166 offset:49152
	ds_read_b128 v[220:223], v166 offset:50176
	ds_read_b128 v[224:227], v166 offset:51200
	ds_read_b128 v[228:231], v166 offset:52224
	ds_read_b128 v[232:235], v166 offset:53248
	ds_read_b128 v[236:239], v166 offset:54272
	ds_read_b128 v[240:243], v166 offset:55296
	ds_read_b128 v[244:247], v166 offset:56320
	global_load_lds_dwordx4 v[192:193], off
	s_add_i32 m0, s46, 0x2000
	s_add_u32 s44, s44, 0x80080
	v_lshl_add_u64 v[192:193], v[248:249], 0, s[56:57]
	s_addc_u32 s45, s45, 0
	s_add_i32 s46, s58, s0
	global_load_lds_dwordx4 v[192:193], off
	v_lshl_add_u64 v[192:193], s[44:45], 0, v[0:1]
	s_mov_b32 m0, s46
	s_nop 0
	global_load_lds_dwordx4 v[192:193], off
	v_lshl_add_u64 v[192:193], s[44:45], 0, v[130:131]
	s_add_i32 m0, s46, 0x2000
	s_nop 0
	global_load_lds_dwordx4 v[192:193], off
	v_lshl_add_u64 v[192:193], v[250:251], 0, s[56:57]
	s_mov_b32 m0, s11
	s_nop 0
	global_load_lds_dwordx4 v[192:193], off
	v_lshl_add_u64 v[192:193], v[200:201], 0, s[56:57]
	s_mov_b32 m0, s26
	s_nop 0
	global_load_lds_dwordx4 v[192:193], off
	s_waitcnt vmcnt(8)
	s_waitcnt lgkmcnt(0)
	s_setprio 1
	s_barrier
	v_mfma_f32_16x16x32_bf16 v[62:65], v[142:145], v[216:219], v[62:65]
	v_mfma_f32_16x16x32_bf16 v[58:61], v[172:175], v[216:219], v[58:61]
	v_mfma_f32_16x16x32_bf16 v[50:53], v[142:145], v[224:227], v[50:53]
	v_mfma_f32_16x16x32_bf16 v[42:45], v[172:175], v[224:227], v[42:45]
	v_mfma_f32_16x16x32_bf16 v[34:37], v[142:145], v[232:235], v[34:37]
	v_mfma_f32_16x16x32_bf16 v[26:29], v[172:175], v[232:235], v[26:29]
	v_mfma_f32_16x16x32_bf16 v[18:21], v[142:145], v[240:243], v[18:21]
	v_mfma_f32_16x16x32_bf16 v[10:13], v[172:175], v[240:243], v[10:13]
	v_mfma_f32_16x16x32_bf16 v[62:65], v[168:171], v[220:223], v[62:65]
	v_mfma_f32_16x16x32_bf16 v[58:61], v[176:179], v[220:223], v[58:61]
	v_mfma_f32_16x16x32_bf16 v[50:53], v[168:171], v[228:231], v[50:53]
	v_mfma_f32_16x16x32_bf16 v[42:45], v[176:179], v[228:231], v[42:45]
	v_mfma_f32_16x16x32_bf16 v[34:37], v[168:171], v[236:239], v[34:37]
	v_mfma_f32_16x16x32_bf16 v[26:29], v[176:179], v[236:239], v[26:29]
	v_mfma_f32_16x16x32_bf16 v[18:21], v[168:171], v[244:247], v[18:21]
	v_mfma_f32_16x16x32_bf16 v[10:13], v[176:179], v[244:247], v[10:13]
	s_setprio 0
	s_setprio 1
	v_mfma_f32_16x16x32_bf16 v[54:57], v[180:183], v[216:219], v[54:57]
	v_mfma_f32_16x16x32_bf16 v[46:49], v[188:191], v[216:219], v[46:49]
	v_mfma_f32_16x16x32_bf16 v[38:41], v[180:183], v[224:227], v[38:41]
	v_mfma_f32_16x16x32_bf16 v[30:33], v[188:191], v[224:227], v[30:33]
	v_mfma_f32_16x16x32_bf16 v[22:25], v[180:183], v[232:235], v[22:25]
	v_mfma_f32_16x16x32_bf16 v[14:17], v[188:191], v[232:235], v[14:17]
	v_mfma_f32_16x16x32_bf16 v[6:9], v[180:183], v[240:243], v[6:9]
	v_mfma_f32_16x16x32_bf16 v[2:5], v[188:191], v[240:243], v[2:5]
	v_mfma_f32_16x16x32_bf16 v[54:57], v[184:187], v[220:223], v[54:57]
	v_mfma_f32_16x16x32_bf16 v[46:49], v[204:207], v[220:223], v[46:49]
	v_mfma_f32_16x16x32_bf16 v[38:41], v[184:187], v[228:231], v[38:41]
	v_mfma_f32_16x16x32_bf16 v[30:33], v[204:207], v[228:231], v[30:33]
	v_mfma_f32_16x16x32_bf16 v[22:25], v[184:187], v[236:239], v[22:25]
	v_mfma_f32_16x16x32_bf16 v[14:17], v[204:207], v[236:239], v[14:17]
	v_mfma_f32_16x16x32_bf16 v[6:9], v[184:187], v[244:247], v[6:9]
	v_mfma_f32_16x16x32_bf16 v[2:5], v[204:207], v[244:247], v[2:5]
	s_barrier
	s_setprio 0
	s_add_i32 s54, s54, 2
	s_add_u32 s24, s24, 0x100
	s_addc_u32 s25, s25, 0
	s_add_u32 s50, s50, 0x100
	s_addc_u32 s51, s51, 0
	s_cmp_gt_u32 s54, 29
	s_cbranch_scc0 .LBB0_146
	s_and_b64 vcc, exec, s[16:17]
	s_cbranch_vccz .LBB0_149
	s_barrier

; #define PG8_STAGE(bufoff, gbase, voff) do { _Pragma("unroll") for (int _i = 0; _i < 2; ++_i) \
;         __builtin_amdgcn_global_load_lds((const unsigned*)((const char*)(gbase) + (voff)[_i]), (PG8_LAS unsigned*)(lds + (bufoff) + ldsw + _i * 8192), 16, 0, 0); } while (0)
; #define PG8_LDA(dst, b, h) do { _Pragma("unroll") for (int m = 0; m < 4; ++m) _Pragma("unroll") for (int k = 0; k < 2; ++k) dst[m][k] = *(const PG8_LAS bf16x8*)(lds + PG8_SA(b, h) + aoff + m * 2048 + k * 1024); } while (0)
; #define PG8_LDB(dst, b, h) do { _Pragma("unroll") for (int n = 0; n < 2; ++n) _Pragma("unroll") for (int k = 0; k < 2; ++k) dst[n][k] = *(const PG8_LAS bf16x8*)(lds + PG8_SB(b, h) + boff + n * 2048 + k * 1024); } while (0)
; #define PG8_MMA(ai, bj, At, Bt) do { __builtin_amdgcn_s_setprio(1); _Pragma("unroll") for (int m = 0; m < 4; ++m) _Pragma("unroll") for (int n = 0; n < 2; ++n) _Pragma("unroll") for (int k = 0; k < 2; ++k) \
;         acc[ai][bj][m][n] = __builtin_amdgcn_mfma_f32_16x16x32_bf16(Bt[n][k], At[m][k], acc[ai][bj][m][n], 0, 0, 0); __builtin_amdgcn_s_setprio(0); } while (0)
; #define PG8_WAIT_V(n) asm volatile("s_waitcnt vmcnt(" #n ")" ::: "memory")
; #define PG8_WAIT_L(n) asm volatile("s_waitcnt lgkmcnt(" #n ")" ::: "memory")
; template <class Epi, class Sched, bool ALIGN_EPI = false, bool SP2 = false>
; __device__ __forceinline__ void gemm_phase(PG8_LAS unsigned char* lds, const Gemm g, const Sched& S, const Epi& E) {
;     ...
;             const bool last = (t == nt - 2);
;             const char* a1 = cA + (size_t)(t + 1) * kstep;
;             const char* a2 = last ? nA : cA + (size_t)(t + 2) * kstep; const char* b2 = last ? nB : cB + (size_t)(t + 2) * kstep;
;             const char* a3 = a2 + kstep; const char* b3 = b2 + kstep;
;             if (last && has_next) S.a_ready(nxt);
;             if constexpr (SP2) {
;             PG8_LDB(B0, 0, 0); PG8_LDB(B1, 0, 1); PG8_SCHED; PG8_LDA(At, 0, 0); PG8_STAGE(PG8_SA(1, 1), a1 + hstep, voffA);
;             PG8_WAIT_V(8); PG8_WAIT_L(0); PG8_BAR; PG8_MMA(0, 0, At, B0); PG8_MMA(0, 1, At, B1); PG8_BAR; PG8_SCHED;
;             PG8_LDA(At, 0, 1); PG8_STAGE(PG8_SB(0, 0), b2, voffB); PG8_STAGE(PG8_SB(0, 1), b2 + hstep, voffB); PG8_STAGE(PG8_SA(0, 0), a2, voffA);
;             PG8_WAIT_V(8); PG8_WAIT_L(0); PG8_BAR; PG8_MMA(1, 0, At, B0); PG8_MMA(1, 1, At, B1); PG8_BAR; PG8_SCHED;
.LBB0_489:
	s_add_u32 s50, s24, 0xfff80080
	s_addc_u32 s51, s25, -1
	s_add_i32 s66, 0, 0x10000
	s_cmp_eq_u32 s63, 28
	s_cselect_b32 s59, s15, s51
	s_cselect_b32 s58, s23, s50
	s_cselect_b32 s51, s21, s62
	s_cselect_b32 s50, s26, s27
	s_add_i32 s68, 0, 0x14000
	v_add_u32_e32 v152, s66, v163
	v_add_u32_e32 v160, s68, v163
	ds_read_b128 v[130:133], v152
	ds_read_b128 v[134:137], v152 offset:1024
	ds_read_b128 v[138:141], v152 offset:2048
	ds_read_b128 v[152:155], v152 offset:3072
	ds_read_b128 v[156:159], v160
	ds_read_b128 v[166:169], v160 offset:1024
	ds_read_b128 v[170:173], v160 offset:2048
	ds_read_b128 v[174:177], v160 offset:3072
	v_lshl_add_u64 v[160:161], s[24:25], 0, v[148:149]
	s_add_i32 m0, s3, 0xc000
	ds_read_b128 v[178:181], v165
	ds_read_b128 v[182:185], v165 offset:1024
	ds_read_b128 v[186:189], v165 offset:2048
	ds_read_b128 v[190:193], v165 offset:3072
	ds_read_b128 v[204:207], v165 offset:4096
	ds_read_b128 v[218:221], v165 offset:5120
	ds_read_b128 v[222:225], v165 offset:6144
	ds_read_b128 v[226:229], v165 offset:7168
	global_load_lds_dwordx4 v[160:161], off
	v_lshl_add_u64 v[160:161], s[24:25], 0, v[150:151]
	s_add_i32 m0, s3, 0xe000
	s_nop 0
	global_load_lds_dwordx4 v[160:161], off
	s_waitcnt vmcnt(8)
	s_waitcnt lgkmcnt(0)
	s_setprio 1
	s_barrier
	v_mfma_f32_16x16x32_bf16 v[126:129], v[130:133], v[178:181], v[126:129]
	v_mfma_f32_16x16x32_bf16 v[122:125], v[138:141], v[178:181], v[122:125]
	v_mfma_f32_16x16x32_bf16 v[110:113], v[130:133], v[186:189], v[110:113]
	v_mfma_f32_16x16x32_bf16 v[106:109], v[138:141], v[186:189], v[106:109]
	v_mfma_f32_16x16x32_bf16 v[94:97], v[130:133], v[204:207], v[94:97]
	v_mfma_f32_16x16x32_bf16 v[90:93], v[138:141], v[204:207], v[90:93]
	v_mfma_f32_16x16x32_bf16 v[78:81], v[130:133], v[222:225], v[78:81]
	v_mfma_f32_16x16x32_bf16 v[74:77], v[138:141], v[222:225], v[74:77]
	v_mfma_f32_16x16x32_bf16 v[126:129], v[134:137], v[182:185], v[126:129]
	v_mfma_f32_16x16x32_bf16 v[122:125], v[152:155], v[182:185], v[122:125]
	v_mfma_f32_16x16x32_bf16 v[110:113], v[134:137], v[190:193], v[110:113]
	v_mfma_f32_16x16x32_bf16 v[106:109], v[152:155], v[190:193], v[106:109]
	v_mfma_f32_16x16x32_bf16 v[94:97], v[134:137], v[218:221], v[94:97]
	v_mfma_f32_16x16x32_bf16 v[90:93], v[152:155], v[218:221], v[90:93]
	v_mfma_f32_16x16x32_bf16 v[78:81], v[134:137], v[226:229], v[78:81]
	v_mfma_f32_16x16x32_bf16 v[74:77], v[152:155], v[226:229], v[74:77]
	s_setprio 0
	s_setprio 1
	v_mfma_f32_16x16x32_bf16 v[118:121], v[156:159], v[178:181], v[118:121]
	v_mfma_f32_16x16x32_bf16 v[114:117], v[170:173], v[178:181], v[114:117]
	v_mfma_f32_16x16x32_bf16 v[102:105], v[156:159], v[186:189], v[102:105]
	v_mfma_f32_16x16x32_bf16 v[98:101], v[170:173], v[186:189], v[98:101]
	v_mfma_f32_16x16x32_bf16 v[86:89], v[156:159], v[204:207], v[86:89]
	v_mfma_f32_16x16x32_bf16 v[82:85], v[170:173], v[204:207], v[82:85]
	v_mfma_f32_16x16x32_bf16 v[70:73], v[156:159], v[222:225], v[70:73]
	v_mfma_f32_16x16x32_bf16 v[66:69], v[170:173], v[222:225], v[66:69]
	v_mfma_f32_16x16x32_bf16 v[118:121], v[166:169], v[182:185], v[118:121]
	v_mfma_f32_16x16x32_bf16 v[114:117], v[174:177], v[182:185], v[114:117]
	v_mfma_f32_16x16x32_bf16 v[102:105], v[166:169], v[190:193], v[102:105]
	v_mfma_f32_16x16x32_bf16 v[98:101], v[174:177], v[190:193], v[98:101]
	v_mfma_f32_16x16x32_bf16 v[86:89], v[166:169], v[218:221], v[86:89]
	v_mfma_f32_16x16x32_bf16 v[82:85], v[174:177], v[218:221], v[82:85]
	v_mfma_f32_16x16x32_bf16 v[70:73], v[166:169], v[226:229], v[70:73]
	v_mfma_f32_16x16x32_bf16 v[66:69], v[174:177], v[226:229], v[66:69]
	s_barrier
	s_setprio 0
	s_add_i32 s66, s66, s2
	v_lshl_add_u64 v[160:161], s[50:51], 0, v[0:1]
	s_mov_b32 m0, s66
	ds_read_b128 v[178:181], v165 offset:16384
	ds_read_b128 v[182:185], v165 offset:17408
	ds_read_b128 v[186:189], v165 offset:18432
	ds_read_b128 v[190:193], v165 offset:19456
	ds_read_b128 v[204:207], v165 offset:20480
	ds_read_b128 v[218:221], v165 offset:21504
	ds_read_b128 v[222:225], v165 offset:22528
	ds_read_b128 v[226:229], v165 offset:23552
	global_load_lds_dwordx4 v[160:161], off
	s_add_i32 m0, s66, 0x2000
	s_add_u32 s66, s50, 0x80000
	v_lshl_add_u64 v[200:201], s[50:51], 0, v[146:147]
	s_addc_u32 s67, s51, 0
	s_add_i32 s68, s68, s2
	global_load_lds_dwordx4 v[200:201], off
	v_lshl_add_u64 v[202:203], s[66:67], 0, v[0:1]
	s_mov_b32 m0, s68
	v_lshl_add_u64 v[230:231], s[58:59], 0, v[144:145]
	global_load_lds_dwordx4 v[202:203], off
	v_lshl_add_u64 v[202:203], s[66:67], 0, v[146:147]
	s_add_i32 m0, s68, 0x2000
	s_nop 0
	global_load_lds_dwordx4 v[202:203], off
	v_lshl_add_u64 v[202:203], s[58:59], 0, v[142:143]
	s_mov_b32 m0, s3
	s_nop 0
	global_load_lds_dwordx4 v[202:203], off
	s_mov_b32 m0, s10
	s_nop 0
	global_load_lds_dwordx4 v[230:231], off
	s_waitcnt vmcnt(8)
	s_waitcnt lgkmcnt(0)
	s_setprio 1
	s_barrier
; #define PG8_STAGE(bufoff, gbase, voff) do { _Pragma("unroll") for (int _i = 0; _i < 2; ++_i) \
;         __builtin_amdgcn_global_load_lds((const unsigned*)((const char*)(gbase) + (voff)[_i]), (PG8_LAS unsigned*)(lds + (bufoff) + ldsw + _i * 8192), 16, 0, 0); } while (0)
; #define PG8_LDA(dst, b, h) do { _Pragma("unroll") for (int m = 0; m < 4; ++m) _Pragma("unroll") for (int k = 0; k < 2; ++k) dst[m][k] = *(const PG8_LAS bf16x8*)(lds + PG8_SA(b, h) + aoff + m * 2048 + k * 1024); } while (0)
; #define PG8_LDB(dst, b, h) do { _Pragma("unroll") for (int n = 0; n < 2; ++n) _Pragma("unroll") for (int k = 0; k < 2; ++k) dst[n][k] = *(const PG8_LAS bf16x8*)(lds + PG8_SB(b, h) + boff + n * 2048 + k * 1024); } while (0)
; #define PG8_MMA(ai, bj, At, Bt) do { __builtin_amdgcn_s_setprio(1); _Pragma("unroll") for (int m = 0; m < 4; ++m) _Pragma("unroll") for (int n = 0; n < 2; ++n) _Pragma("unroll") for (int k = 0; k < 2; ++k) \
;         acc[ai][bj][m][n] = __builtin_amdgcn_mfma_f32_16x16x32_bf16(Bt[n][k], At[m][k], acc[ai][bj][m][n], 0, 0, 0); __builtin_amdgcn_s_setprio(0); } while (0)
; #define PG8_WAIT_V(n) asm volatile("s_waitcnt vmcnt(" #n ")" ::: "memory")
; #define PG8_WAIT_L(n) asm volatile("s_waitcnt lgkmcnt(" #n ")" ::: "memory")
; #define PG8_BAR __builtin_amdgcn_s_barrier()
; #define PG8_SCHED __builtin_amdgcn_sched_barrier(0)
; template <class Epi, class Sched, bool ALIGN_EPI = false, bool SP2 = false>
; __device__ __forceinline__ void gemm_phase(PG8_LAS unsigned char* lds, const Gemm g, const Sched& S, const Epi& E) {
;     ...
;             PG8_WAIT_V(8); PG8_WAIT_L(0); PG8_BAR; PG8_MMA(1, 0, At, B0); PG8_MMA(1, 1, At, B1); PG8_BAR; PG8_SCHED;
;             PG8_LDB(B0, 1, 0); PG8_LDB(B1, 1, 1); PG8_SCHED; PG8_LDA(At, 1, 0); PG8_STAGE(PG8_SA(0, 1), a2 + hstep, voffA);
;             PG8_WAIT_V(8); PG8_WAIT_L(0); PG8_BAR; PG8_MMA(0, 0, At, B0); PG8_MMA(0, 1, At, B1); PG8_BAR; PG8_SCHED;
	v_mfma_f32_16x16x32_bf16 v[62:65], v[130:133], v[178:181], v[62:65]
	v_mfma_f32_16x16x32_bf16 v[58:61], v[138:141], v[178:181], v[58:61]
	v_mfma_f32_16x16x32_bf16 v[46:49], v[130:133], v[186:189], v[46:49]
	v_mfma_f32_16x16x32_bf16 v[42:45], v[138:141], v[186:189], v[42:45]
	v_mfma_f32_16x16x32_bf16 v[30:33], v[130:133], v[204:207], v[30:33]
	v_mfma_f32_16x16x32_bf16 v[26:29], v[138:141], v[204:207], v[26:29]
	v_mfma_f32_16x16x32_bf16 v[14:17], v[130:133], v[222:225], v[14:17]
	v_mfma_f32_16x16x32_bf16 v[10:13], v[138:141], v[222:225], v[10:13]
	v_mfma_f32_16x16x32_bf16 v[62:65], v[134:137], v[182:185], v[62:65]
	v_mfma_f32_16x16x32_bf16 v[58:61], v[152:155], v[182:185], v[58:61]
	v_mfma_f32_16x16x32_bf16 v[46:49], v[134:137], v[190:193], v[46:49]
	v_mfma_f32_16x16x32_bf16 v[42:45], v[152:155], v[190:193], v[42:45]
	v_mfma_f32_16x16x32_bf16 v[30:33], v[134:137], v[218:221], v[30:33]
	v_mfma_f32_16x16x32_bf16 v[26:29], v[152:155], v[218:221], v[26:29]
	v_mfma_f32_16x16x32_bf16 v[14:17], v[134:137], v[226:229], v[14:17]
	v_mfma_f32_16x16x32_bf16 v[10:13], v[152:155], v[226:229], v[10:13]
	s_setprio 0
	s_setprio 1
	v_mfma_f32_16x16x32_bf16 v[54:57], v[156:159], v[178:181], v[54:57]
	v_mfma_f32_16x16x32_bf16 v[50:53], v[170:173], v[178:181], v[50:53]
	v_mfma_f32_16x16x32_bf16 v[38:41], v[156:159], v[186:189], v[38:41]
	v_mfma_f32_16x16x32_bf16 v[34:37], v[170:173], v[186:189], v[34:37]
	v_mfma_f32_16x16x32_bf16 v[22:25], v[156:159], v[204:207], v[22:25]
	v_mfma_f32_16x16x32_bf16 v[18:21], v[170:173], v[204:207], v[18:21]
	v_mfma_f32_16x16x32_bf16 v[6:9], v[156:159], v[222:225], v[6:9]
	v_mfma_f32_16x16x32_bf16 v[2:5], v[170:173], v[222:225], v[2:5]
	v_mfma_f32_16x16x32_bf16 v[54:57], v[166:169], v[182:185], v[54:57]
	v_mfma_f32_16x16x32_bf16 v[50:53], v[174:177], v[182:185], v[50:53]
	v_mfma_f32_16x16x32_bf16 v[38:41], v[166:169], v[190:193], v[38:41]
	v_mfma_f32_16x16x32_bf16 v[34:37], v[174:177], v[190:193], v[34:37]
	v_mfma_f32_16x16x32_bf16 v[22:25], v[166:169], v[218:221], v[22:25]
	v_mfma_f32_16x16x32_bf16 v[18:21], v[174:177], v[218:221], v[18:21]
	v_mfma_f32_16x16x32_bf16 v[6:9], v[166:169], v[226:229], v[6:9]
	v_mfma_f32_16x16x32_bf16 v[2:5], v[174:177], v[226:229], v[2:5]
	s_barrier
	s_setprio 0
	s_add_i32 s66, 0, 0x18000
	s_add_i32 s67, 0, 0x1c000
	v_add_u32_e32 v152, s66, v163
	v_add_u32_e32 v174, s67, v163
	ds_read_b128 v[130:133], v152
	ds_read_b128 v[134:137], v152 offset:1024
	ds_read_b128 v[138:141], v152 offset:2048
	ds_read_b128 v[152:155], v152 offset:3072
	ds_read_b128 v[156:159], v174
	ds_read_b128 v[166:169], v174 offset:1024
	ds_read_b128 v[170:173], v174 offset:2048
	ds_read_b128 v[174:177], v174 offset:3072
	s_add_u32 s58, s58, 0x80000
	s_addc_u32 s59, s59, 0
	s_mov_b32 m0, s11
	v_lshl_add_u64 v[232:233], s[58:59], 0, v[142:143]
	ds_read_b128 v[178:181], v165 offset:32768
	ds_read_b128 v[182:185], v165 offset:33792
	ds_read_b128 v[186:189], v165 offset:34816
	ds_read_b128 v[190:193], v165 offset:35840
	ds_read_b128 v[204:207], v165 offset:36864
	ds_read_b128 v[218:221], v165 offset:37888
	ds_read_b128 v[222:225], v165 offset:38912
	ds_read_b128 v[226:229], v165 offset:39936
	global_load_lds_dwordx4 v[232:233], off
	v_lshl_add_u64 v[232:233], s[58:59], 0, v[144:145]
	s_mov_b32 m0, s33
	s_nop 0
	global_load_lds_dwordx4 v[232:233], off
	s_waitcnt vmcnt(8)
	s_waitcnt lgkmcnt(0)
	s_setprio 1
	s_barrier
	v_mfma_f32_16x16x32_bf16 v[126:129], v[130:133], v[178:181], v[126:129]
	v_mfma_f32_16x16x32_bf16 v[122:125], v[138:141], v[178:181], v[122:125]
	v_mfma_f32_16x16x32_bf16 v[110:113], v[130:133], v[186:189], v[110:113]
	v_mfma_f32_16x16x32_bf16 v[106:109], v[138:141], v[186:189], v[106:109]
	v_mfma_f32_16x16x32_bf16 v[94:97], v[130:133], v[204:207], v[94:97]
	v_mfma_f32_16x16x32_bf16 v[90:93], v[138:141], v[204:207], v[90:93]
	v_mfma_f32_16x16x32_bf16 v[78:81], v[130:133], v[222:225], v[78:81]
	v_mfma_f32_16x16x32_bf16 v[74:77], v[138:141], v[222:225], v[74:77]
	v_mfma_f32_16x16x32_bf16 v[126:129], v[134:137], v[182:185], v[126:129]
	v_mfma_f32_16x16x32_bf16 v[122:125], v[152:155], v[182:185], v[122:125]
	v_mfma_f32_16x16x32_bf16 v[110:113], v[134:137], v[190:193], v[110:113]
	v_mfma_f32_16x16x32_bf16 v[106:109], v[152:155], v[190:193], v[106:109]
	v_mfma_f32_16x16x32_bf16 v[94:97], v[134:137], v[218:221], v[94:97]
	v_mfma_f32_16x16x32_bf16 v[90:93], v[152:155], v[218:221], v[90:93]
	v_mfma_f32_16x16x32_bf16 v[78:81], v[134:137], v[226:229], v[78:81]
	v_mfma_f32_16x16x32_bf16 v[74:77], v[152:155], v[226:229], v[74:77]
	s_setprio 0
	s_setprio 1
	v_mfma_f32_16x16x32_bf16 v[118:121], v[156:159], v[178:181], v[118:121]
	v_mfma_f32_16x16x32_bf16 v[114:117], v[170:173], v[178:181], v[114:117]
	v_mfma_f32_16x16x32_bf16 v[102:105], v[156:159], v[186:189], v[102:105]
	v_mfma_f32_16x16x32_bf16 v[98:101], v[170:173], v[186:189], v[98:101]
	v_mfma_f32_16x16x32_bf16 v[86:89], v[156:159], v[204:207], v[86:89]
	v_mfma_f32_16x16x32_bf16 v[82:85], v[170:173], v[204:207], v[82:85]
	v_mfma_f32_16x16x32_bf16 v[70:73], v[156:159], v[222:225], v[70:73]
	v_mfma_f32_16x16x32_bf16 v[66:69], v[170:173], v[222:225], v[66:69]
	v_mfma_f32_16x16x32_bf16 v[118:121], v[166:169], v[182:185], v[118:121]
	v_mfma_f32_16x16x32_bf16 v[114:117], v[174:177], v[182:185], v[114:117]
	v_mfma_f32_16x16x32_bf16 v[102:105], v[166:169], v[190:193], v[102:105]
	v_mfma_f32_16x16x32_bf16 v[98:101], v[174:177], v[190:193], v[98:101]
	v_mfma_f32_16x16x32_bf16 v[86:89], v[166:169], v[218:221], v[86:89]
	v_mfma_f32_16x16x32_bf16 v[82:85], v[174:177], v[218:221], v[82:85]
	v_mfma_f32_16x16x32_bf16 v[70:73], v[166:169], v[226:229], v[70:73]
	v_mfma_f32_16x16x32_bf16 v[66:69], v[174:177], v[226:229], v[66:69]
	s_barrier
; #define PG8_STAGE(bufoff, gbase, voff) do { _Pragma("unroll") for (int _i = 0; _i < 2; ++_i) \
;         __builtin_amdgcn_global_load_lds((const unsigned*)((const char*)(gbase) + (voff)[_i]), (PG8_LAS unsigned*)(lds + (bufoff) + ldsw + _i * 8192), 16, 0, 0); } while (0)
; #define PG8_LDA(dst, b, h) do { _Pragma("unroll") for (int m = 0; m < 4; ++m) _Pragma("unroll") for (int k = 0; k < 2; ++k) dst[m][k] = *(const PG8_LAS bf16x8*)(lds + PG8_SA(b, h) + aoff + m * 2048 + k * 1024); } while (0)
; #define PG8_MMA(ai, bj, At, Bt) do { __builtin_amdgcn_s_setprio(1); _Pragma("unroll") for (int m = 0; m < 4; ++m) _Pragma("unroll") for (int n = 0; n < 2; ++n) _Pragma("unroll") for (int k = 0; k < 2; ++k) \
;         acc[ai][bj][m][n] = __builtin_amdgcn_mfma_f32_16x16x32_bf16(Bt[n][k], At[m][k], acc[ai][bj][m][n], 0, 0, 0); __builtin_amdgcn_s_setprio(0); } while (0)
; #define PG8_WAIT_V(n) asm volatile("s_waitcnt vmcnt(" #n ")" ::: "memory")
; #define PG8_WAIT_L(n) asm volatile("s_waitcnt lgkmcnt(" #n ")" ::: "memory")
; #define PG8_BAR __builtin_amdgcn_s_barrier()
; #define PG8_SCHED __builtin_amdgcn_sched_barrier(0)
; template <class Epi, class Sched, bool ALIGN_EPI = false, bool SP2 = false>
; __device__ __forceinline__ void gemm_phase(PG8_LAS unsigned char* lds, const Gemm g, const Sched& S, const Epi& E) {
;     ...
;         for (int t = 0; t < nt; t += 2) {
;             const bool last = (t == nt - 2);
;             const char* a1 = cA + (size_t)(t + 1) * kstep;
;             const char* a2 = last ? nA : cA + (size_t)(t + 2) * kstep; const char* b2 = last ? nB : cB + (size_t)(t + 2) * kstep;
;     ...
;             PG8_LDA(At, 1, 1); PG8_STAGE(PG8_SB(1, 0), b3, voffB); PG8_STAGE(PG8_SB(1, 1), b3 + hstep, voffB); PG8_STAGE(PG8_SA(1, 0), a3, voffA);
;             PG8_WAIT_V(8); PG8_WAIT_L(0); PG8_BAR; PG8_MMA(1, 0, At, B0); PG8_MMA(1, 1, At, B1); PG8_BAR; PG8_SCHED;
	s_setprio 0
	s_add_i32 s58, s66, s2
	v_lshl_add_u64 v[160:161], v[160:161], 0, s[56:57]
	s_mov_b32 m0, s58
	ds_read_b128 v[178:181], v165 offset:49152
	ds_read_b128 v[182:185], v165 offset:50176
	ds_read_b128 v[186:189], v165 offset:51200
	ds_read_b128 v[190:193], v165 offset:52224
	ds_read_b128 v[204:207], v165 offset:53248
	ds_read_b128 v[218:221], v165 offset:54272
	ds_read_b128 v[222:225], v165 offset:55296
	ds_read_b128 v[226:229], v165 offset:56320
	global_load_lds_dwordx4 v[160:161], off
	s_add_i32 m0, s58, 0x2000
	s_add_u32 s50, s50, 0x80080
	v_lshl_add_u64 v[160:161], v[200:201], 0, s[56:57]
	s_addc_u32 s51, s51, 0
	s_add_i32 s58, s67, s2
	global_load_lds_dwordx4 v[160:161], off
	v_lshl_add_u64 v[160:161], s[50:51], 0, v[0:1]
	s_mov_b32 m0, s58
	s_nop 0
	global_load_lds_dwordx4 v[160:161], off
	v_lshl_add_u64 v[160:161], s[50:51], 0, v[146:147]
	s_add_i32 m0, s58, 0x2000
	s_nop 0
	global_load_lds_dwordx4 v[160:161], off
	v_lshl_add_u64 v[160:161], v[202:203], 0, s[56:57]
	s_mov_b32 m0, s49
	s_nop 0
	global_load_lds_dwordx4 v[160:161], off
	v_lshl_add_u64 v[160:161], v[230:231], 0, s[56:57]
	s_mov_b32 m0, s54
	s_nop 0
	global_load_lds_dwordx4 v[160:161], off
	s_waitcnt vmcnt(8)
	s_waitcnt lgkmcnt(0)
	s_setprio 1
	s_barrier
	v_mfma_f32_16x16x32_bf16 v[62:65], v[130:133], v[178:181], v[62:65]
	v_mfma_f32_16x16x32_bf16 v[58:61], v[138:141], v[178:181], v[58:61]
	v_mfma_f32_16x16x32_bf16 v[46:49], v[130:133], v[186:189], v[46:49]
	v_mfma_f32_16x16x32_bf16 v[42:45], v[138:141], v[186:189], v[42:45]
	v_mfma_f32_16x16x32_bf16 v[30:33], v[130:133], v[204:207], v[30:33]
	v_mfma_f32_16x16x32_bf16 v[26:29], v[138:141], v[204:207], v[26:29]
	v_mfma_f32_16x16x32_bf16 v[14:17], v[130:133], v[222:225], v[14:17]
	v_mfma_f32_16x16x32_bf16 v[10:13], v[138:141], v[222:225], v[10:13]
	v_mfma_f32_16x16x32_bf16 v[62:65], v[134:137], v[182:185], v[62:65]
	v_mfma_f32_16x16x32_bf16 v[58:61], v[152:155], v[182:185], v[58:61]
	v_mfma_f32_16x16x32_bf16 v[46:49], v[134:137], v[190:193], v[46:49]
	v_mfma_f32_16x16x32_bf16 v[42:45], v[152:155], v[190:193], v[42:45]
	v_mfma_f32_16x16x32_bf16 v[30:33], v[134:137], v[218:221], v[30:33]
	v_mfma_f32_16x16x32_bf16 v[26:29], v[152:155], v[218:221], v[26:29]
	v_mfma_f32_16x16x32_bf16 v[14:17], v[134:137], v[226:229], v[14:17]
	v_mfma_f32_16x16x32_bf16 v[10:13], v[152:155], v[226:229], v[10:13]
	s_setprio 0
	s_setprio 1
	v_mfma_f32_16x16x32_bf16 v[54:57], v[156:159], v[178:181], v[54:57]
	v_mfma_f32_16x16x32_bf16 v[50:53], v[170:173], v[178:181], v[50:53]
	v_mfma_f32_16x16x32_bf16 v[38:41], v[156:159], v[186:189], v[38:41]
	v_mfma_f32_16x16x32_bf16 v[34:37], v[170:173], v[186:189], v[34:37]
	v_mfma_f32_16x16x32_bf16 v[22:25], v[156:159], v[204:207], v[22:25]
	v_mfma_f32_16x16x32_bf16 v[18:21], v[170:173], v[204:207], v[18:21]
	v_mfma_f32_16x16x32_bf16 v[6:9], v[156:159], v[222:225], v[6:9]
	v_mfma_f32_16x16x32_bf16 v[2:5], v[170:173], v[222:225], v[2:5]
	v_mfma_f32_16x16x32_bf16 v[54:57], v[166:169], v[182:185], v[54:57]
	v_mfma_f32_16x16x32_bf16 v[50:53], v[174:177], v[182:185], v[50:53]
	v_mfma_f32_16x16x32_bf16 v[38:41], v[166:169], v[190:193], v[38:41]
	v_mfma_f32_16x16x32_bf16 v[34:37], v[174:177], v[190:193], v[34:37]
	v_mfma_f32_16x16x32_bf16 v[22:25], v[166:169], v[218:221], v[22:25]
	v_mfma_f32_16x16x32_bf16 v[18:21], v[174:177], v[218:221], v[18:21]
	v_mfma_f32_16x16x32_bf16 v[6:9], v[166:169], v[226:229], v[6:9]
	v_mfma_f32_16x16x32_bf16 v[2:5], v[174:177], v[226:229], v[2:5]
	s_barrier
	s_setprio 0
	s_add_i32 s63, s63, 2
	s_add_u32 s24, s24, 0x100
	s_addc_u32 s25, s25, 0
	s_add_u32 s27, s27, 0x100
	s_addc_u32 s62, s62, 0
	s_cmp_gt_u32 s63, 29
	s_cbranch_scc0 .LBB0_489
	s_and_b64 vcc, exec, s[18:19]
	s_cbranch_vccz .LBB0_492
	s_barrier

; #define PG8_STAGE(bufoff, gbase, voff) do { _Pragma("unroll") for (int _i = 0; _i < 2; ++_i) \
;         __builtin_amdgcn_global_load_lds((const unsigned*)((const char*)(gbase) + (voff)[_i]), (PG8_LAS unsigned*)(lds + (bufoff) + ldsw + _i * 8192), 16, 0, 0); } while (0)
; #define PG8_LDA(dst, b, h) do { _Pragma("unroll") for (int m = 0; m < 4; ++m) _Pragma("unroll") for (int k = 0; k < 2; ++k) dst[m][k] = *(const PG8_LAS bf16x8*)(lds + PG8_SA(b, h) + aoff + m * 2048 + k * 1024); } while (0)
; #define PG8_LDB(dst, b, h) do { _Pragma("unroll") for (int n = 0; n < 2; ++n) _Pragma("unroll") for (int k = 0; k < 2; ++k) dst[n][k] = *(const PG8_LAS bf16x8*)(lds + PG8_SB(b, h) + boff + n * 2048 + k * 1024); } while (0)
; #define PG8_MMA(ai, bj, At, Bt) do { __builtin_amdgcn_s_setprio(1); _Pragma("unroll") for (int m = 0; m < 4; ++m) _Pragma("unroll") for (int n = 0; n < 2; ++n) _Pragma("unroll") for (int k = 0; k < 2; ++k) \
;         acc[ai][bj][m][n] = __builtin_amdgcn_mfma_f32_16x16x32_bf16(Bt[n][k], At[m][k], acc[ai][bj][m][n], 0, 0, 0); __builtin_amdgcn_s_setprio(0); } while (0)
; #define PG8_WAIT_V(n) asm volatile("s_waitcnt vmcnt(" #n ")" ::: "memory")
; #define PG8_WAIT_L(n) asm volatile("s_waitcnt lgkmcnt(" #n ")" ::: "memory")
; template <class Epi, class Sched, bool ALIGN_EPI = false, bool SP2 = false>
; __device__ __forceinline__ void gemm_phase(PG8_LAS unsigned char* lds, const Gemm g, const Sched& S, const Epi& E) {
;     ...
;             const bool last = (t == nt - 2);
;             const char* a1 = cA + (size_t)(t + 1) * kstep;
;             const char* a2 = last ? nA : cA + (size_t)(t + 2) * kstep; const char* b2 = last ? nB : cB + (size_t)(t + 2) * kstep;
;             const char* a3 = a2 + kstep; const char* b3 = b2 + kstep;
;             if (last && has_next) S.a_ready(nxt);
;             if constexpr (SP2) {
;             PG8_LDB(B0, 0, 0); PG8_LDB(B1, 0, 1); PG8_SCHED; PG8_LDA(At, 0, 0); PG8_STAGE(PG8_SA(1, 1), a1 + hstep, voffA);
;             PG8_WAIT_V(8); PG8_WAIT_L(0); PG8_BAR; PG8_MMA(0, 0, At, B0); PG8_MMA(0, 1, At, B1); PG8_BAR; PG8_SCHED;
;             PG8_LDA(At, 0, 1); PG8_STAGE(PG8_SB(0, 0), b2, voffB); PG8_STAGE(PG8_SB(0, 1), b2 + hstep, voffB); PG8_STAGE(PG8_SA(0, 0), a2, voffA);
;             PG8_WAIT_V(8); PG8_WAIT_L(0); PG8_BAR; PG8_MMA(1, 0, At, B0); PG8_MMA(1, 1, At, B1); PG8_BAR; PG8_SCHED;
.LBB0_516:
	s_add_u32 s20, s18, 0x100
	s_addc_u32 s21, s19, 0
	s_cmp_lg_u32 s38, 4
	s_cselect_b32 s22, s20, 0
	s_cselect_b32 s23, s21, 0
	s_add_u32 s24, s16, s22
	s_addc_u32 s25, s17, s23
	s_add_i32 s39, 0, 0x10000
	s_add_u32 s22, s14, s22
	s_addc_u32 s23, s15, s23
	s_add_i32 s40, 0, 0x14000
	v_add_u32_e32 v156, s39, v142
	v_add_u32_e32 v172, s40, v142
	ds_read_b128 v[144:147], v156
	ds_read_b128 v[148:151], v156 offset:1024
	ds_read_b128 v[152:155], v156 offset:2048
	ds_read_b128 v[156:159], v156 offset:3072
	ds_read_b128 v[160:163], v172
	ds_read_b128 v[164:167], v172 offset:1024
	ds_read_b128 v[168:171], v172 offset:2048
	ds_read_b128 v[172:175], v172 offset:3072
	v_lshl_add_u64 v[192:193], v[138:139], 0, s[18:19]
	s_add_i32 m0, s1, 0xc000
	ds_read_b128 v[176:179], v143
	ds_read_b128 v[180:183], v143 offset:1024
	ds_read_b128 v[184:187], v143 offset:2048
	ds_read_b128 v[188:191], v143 offset:3072
	ds_read_b128 v[204:207], v143 offset:4096
	ds_read_b128 v[220:223], v143 offset:5120
	ds_read_b128 v[224:227], v143 offset:6144
	ds_read_b128 v[228:231], v143 offset:7168
	global_load_lds_dwordx4 v[192:193], off
	v_lshl_add_u64 v[192:193], v[140:141], 0, s[18:19]
	s_add_i32 m0, s1, 0xe000
	s_nop 0
	global_load_lds_dwordx4 v[192:193], off
	s_waitcnt vmcnt(8)
	s_waitcnt lgkmcnt(0)
	s_setprio 1
	s_barrier
	v_mfma_f32_16x16x32_bf16 v[58:61], v[144:147], v[176:179], v[58:61]
	v_mfma_f32_16x16x32_bf16 v[62:65], v[152:155], v[176:179], v[62:65]
	v_mfma_f32_16x16x32_bf16 v[42:45], v[144:147], v[184:187], v[42:45]
	v_mfma_f32_16x16x32_bf16 v[46:49], v[152:155], v[184:187], v[46:49]
	v_mfma_f32_16x16x32_bf16 v[26:29], v[144:147], v[204:207], v[26:29]
	v_mfma_f32_16x16x32_bf16 v[30:33], v[152:155], v[204:207], v[30:33]
	v_mfma_f32_16x16x32_bf16 v[10:13], v[144:147], v[224:227], v[10:13]
	v_mfma_f32_16x16x32_bf16 v[14:17], v[152:155], v[224:227], v[14:17]
	v_mfma_f32_16x16x32_bf16 v[58:61], v[148:151], v[180:183], v[58:61]
	v_mfma_f32_16x16x32_bf16 v[62:65], v[156:159], v[180:183], v[62:65]
	v_mfma_f32_16x16x32_bf16 v[42:45], v[148:151], v[188:191], v[42:45]
	v_mfma_f32_16x16x32_bf16 v[46:49], v[156:159], v[188:191], v[46:49]
	v_mfma_f32_16x16x32_bf16 v[26:29], v[148:151], v[220:223], v[26:29]
	v_mfma_f32_16x16x32_bf16 v[30:33], v[156:159], v[220:223], v[30:33]
	v_mfma_f32_16x16x32_bf16 v[10:13], v[148:151], v[228:231], v[10:13]
	v_mfma_f32_16x16x32_bf16 v[14:17], v[156:159], v[228:231], v[14:17]
	s_setprio 0
	s_setprio 1
	v_mfma_f32_16x16x32_bf16 v[50:53], v[160:163], v[176:179], v[50:53]
	v_mfma_f32_16x16x32_bf16 v[54:57], v[168:171], v[176:179], v[54:57]
	v_mfma_f32_16x16x32_bf16 v[34:37], v[160:163], v[184:187], v[34:37]
	v_mfma_f32_16x16x32_bf16 v[38:41], v[168:171], v[184:187], v[38:41]
	v_mfma_f32_16x16x32_bf16 v[18:21], v[160:163], v[204:207], v[18:21]
	v_mfma_f32_16x16x32_bf16 v[22:25], v[168:171], v[204:207], v[22:25]
	v_mfma_f32_16x16x32_bf16 v[2:5], v[160:163], v[224:227], v[2:5]
	v_mfma_f32_16x16x32_bf16 v[6:9], v[168:171], v[224:227], v[6:9]
	v_mfma_f32_16x16x32_bf16 v[50:53], v[164:167], v[180:183], v[50:53]
	v_mfma_f32_16x16x32_bf16 v[54:57], v[172:175], v[180:183], v[54:57]
	v_mfma_f32_16x16x32_bf16 v[34:37], v[164:167], v[188:191], v[34:37]
	v_mfma_f32_16x16x32_bf16 v[38:41], v[172:175], v[188:191], v[38:41]
	v_mfma_f32_16x16x32_bf16 v[18:21], v[164:167], v[220:223], v[18:21]
	v_mfma_f32_16x16x32_bf16 v[22:25], v[172:175], v[220:223], v[22:25]
	v_mfma_f32_16x16x32_bf16 v[2:5], v[164:167], v[228:231], v[2:5]
	v_mfma_f32_16x16x32_bf16 v[6:9], v[172:175], v[228:231], v[6:9]
	s_barrier
	s_setprio 0
	s_add_i32 s18, s39, s3
	v_lshl_add_u64 v[192:193], s[22:23], 0, v[0:1]
	s_mov_b32 m0, s18
	ds_read_b128 v[176:179], v143 offset:16384
	ds_read_b128 v[180:183], v143 offset:17408
	ds_read_b128 v[184:187], v143 offset:18432
	ds_read_b128 v[188:191], v143 offset:19456
	ds_read_b128 v[204:207], v143 offset:20480
	ds_read_b128 v[220:223], v143 offset:21504
	ds_read_b128 v[224:227], v143 offset:22528
	ds_read_b128 v[228:231], v143 offset:23552
	global_load_lds_dwordx4 v[192:193], off
	s_add_i32 m0, s18, 0x2000
	s_add_u32 s18, s22, 0x80000
	v_lshl_add_u64 v[200:201], s[22:23], 0, v[136:137]
	s_addc_u32 s19, s23, 0
	s_add_i32 s39, s40, s3
	global_load_lds_dwordx4 v[200:201], off
	v_lshl_add_u64 v[202:203], s[18:19], 0, v[0:1]
	s_mov_b32 m0, s39
	v_lshl_add_u64 v[232:233], s[24:25], 0, v[134:135]
	global_load_lds_dwordx4 v[202:203], off
	v_lshl_add_u64 v[202:203], s[18:19], 0, v[136:137]
	s_add_i32 m0, s39, 0x2000
	s_nop 0
	global_load_lds_dwordx4 v[202:203], off
	v_lshl_add_u64 v[202:203], s[24:25], 0, v[132:133]
	s_mov_b32 m0, s1
	s_nop 0
	global_load_lds_dwordx4 v[202:203], off
	s_mov_b32 m0, s10
	s_nop 0
	global_load_lds_dwordx4 v[232:233], off
	s_waitcnt vmcnt(8)
	s_waitcnt lgkmcnt(0)
	s_setprio 1
	s_barrier
; #define PG8_STAGE(bufoff, gbase, voff) do { _Pragma("unroll") for (int _i = 0; _i < 2; ++_i) \
;         __builtin_amdgcn_global_load_lds((const unsigned*)((const char*)(gbase) + (voff)[_i]), (PG8_LAS unsigned*)(lds + (bufoff) + ldsw + _i * 8192), 16, 0, 0); } while (0)
; #define PG8_LDA(dst, b, h) do { _Pragma("unroll") for (int m = 0; m < 4; ++m) _Pragma("unroll") for (int k = 0; k < 2; ++k) dst[m][k] = *(const PG8_LAS bf16x8*)(lds + PG8_SA(b, h) + aoff + m * 2048 + k * 1024); } while (0)
; #define PG8_LDB(dst, b, h) do { _Pragma("unroll") for (int n = 0; n < 2; ++n) _Pragma("unroll") for (int k = 0; k < 2; ++k) dst[n][k] = *(const PG8_LAS bf16x8*)(lds + PG8_SB(b, h) + boff + n * 2048 + k * 1024); } while (0)
; #define PG8_MMA(ai, bj, At, Bt) do { __builtin_amdgcn_s_setprio(1); _Pragma("unroll") for (int m = 0; m < 4; ++m) _Pragma("unroll") for (int n = 0; n < 2; ++n) _Pragma("unroll") for (int k = 0; k < 2; ++k) \
;         acc[ai][bj][m][n] = __builtin_amdgcn_mfma_f32_16x16x32_bf16(Bt[n][k], At[m][k], acc[ai][bj][m][n], 0, 0, 0); __builtin_amdgcn_s_setprio(0); } while (0)
; #define PG8_WAIT_V(n) asm volatile("s_waitcnt vmcnt(" #n ")" ::: "memory")
; #define PG8_WAIT_L(n) asm volatile("s_waitcnt lgkmcnt(" #n ")" ::: "memory")
; #define PG8_BAR __builtin_amdgcn_s_barrier()
; #define PG8_SCHED __builtin_amdgcn_sched_barrier(0)
; template <class Epi, class Sched, bool ALIGN_EPI = false, bool SP2 = false>
; __device__ __forceinline__ void gemm_phase(PG8_LAS unsigned char* lds, const Gemm g, const Sched& S, const Epi& E) {
;     ...
;             PG8_WAIT_V(8); PG8_WAIT_L(0); PG8_BAR; PG8_MMA(1, 0, At, B0); PG8_MMA(1, 1, At, B1); PG8_BAR; PG8_SCHED;
;             PG8_LDB(B0, 1, 0); PG8_LDB(B1, 1, 1); PG8_SCHED; PG8_LDA(At, 1, 0); PG8_STAGE(PG8_SA(0, 1), a2 + hstep, voffA);
;             PG8_WAIT_V(8); PG8_WAIT_L(0); PG8_BAR; PG8_MMA(0, 0, At, B0); PG8_MMA(0, 1, At, B1); PG8_BAR; PG8_SCHED;
	v_mfma_f32_16x16x32_bf16 v[90:93], v[144:147], v[176:179], v[90:93]
	v_mfma_f32_16x16x32_bf16 v[94:97], v[152:155], v[176:179], v[94:97]
	v_mfma_f32_16x16x32_bf16 v[74:77], v[144:147], v[184:187], v[74:77]
	v_mfma_f32_16x16x32_bf16 v[78:81], v[152:155], v[184:187], v[78:81]
	v_mfma_f32_16x16x32_bf16 v[122:125], v[144:147], v[204:207], v[122:125]
	v_mfma_f32_16x16x32_bf16 v[126:129], v[152:155], v[204:207], v[126:129]
	v_mfma_f32_16x16x32_bf16 v[106:109], v[144:147], v[224:227], v[106:109]
	v_mfma_f32_16x16x32_bf16 v[110:113], v[152:155], v[224:227], v[110:113]
	v_mfma_f32_16x16x32_bf16 v[90:93], v[148:151], v[180:183], v[90:93]
	v_mfma_f32_16x16x32_bf16 v[94:97], v[156:159], v[180:183], v[94:97]
	v_mfma_f32_16x16x32_bf16 v[74:77], v[148:151], v[188:191], v[74:77]
	v_mfma_f32_16x16x32_bf16 v[78:81], v[156:159], v[188:191], v[78:81]
	v_mfma_f32_16x16x32_bf16 v[122:125], v[148:151], v[220:223], v[122:125]
	v_mfma_f32_16x16x32_bf16 v[126:129], v[156:159], v[220:223], v[126:129]
	v_mfma_f32_16x16x32_bf16 v[106:109], v[148:151], v[228:231], v[106:109]
	v_mfma_f32_16x16x32_bf16 v[110:113], v[156:159], v[228:231], v[110:113]
	s_setprio 0
	s_setprio 1
	v_mfma_f32_16x16x32_bf16 v[82:85], v[160:163], v[176:179], v[82:85]
	v_mfma_f32_16x16x32_bf16 v[86:89], v[168:171], v[176:179], v[86:89]
	v_mfma_f32_16x16x32_bf16 v[66:69], v[160:163], v[184:187], v[66:69]
	v_mfma_f32_16x16x32_bf16 v[70:73], v[168:171], v[184:187], v[70:73]
	v_mfma_f32_16x16x32_bf16 v[114:117], v[160:163], v[204:207], v[114:117]
	v_mfma_f32_16x16x32_bf16 v[118:121], v[168:171], v[204:207], v[118:121]
	v_mfma_f32_16x16x32_bf16 v[102:105], v[160:163], v[224:227], v[102:105]
	v_mfma_f32_16x16x32_bf16 v[98:101], v[168:171], v[224:227], v[98:101]
	v_mfma_f32_16x16x32_bf16 v[82:85], v[164:167], v[180:183], v[82:85]
	v_mfma_f32_16x16x32_bf16 v[86:89], v[172:175], v[180:183], v[86:89]
	v_mfma_f32_16x16x32_bf16 v[66:69], v[164:167], v[188:191], v[66:69]
	v_mfma_f32_16x16x32_bf16 v[70:73], v[172:175], v[188:191], v[70:73]
	v_mfma_f32_16x16x32_bf16 v[114:117], v[164:167], v[220:223], v[114:117]
	v_mfma_f32_16x16x32_bf16 v[118:121], v[172:175], v[220:223], v[118:121]
	v_mfma_f32_16x16x32_bf16 v[102:105], v[164:167], v[228:231], v[102:105]
	v_mfma_f32_16x16x32_bf16 v[98:101], v[172:175], v[228:231], v[98:101]
	s_barrier
	s_setprio 0
	s_add_i32 s39, 0, 0x18000
	s_add_i32 s40, 0, 0x1c000
	v_add_u32_e32 v156, s39, v142
	v_add_u32_e32 v172, s40, v142
	ds_read_b128 v[144:147], v156
	ds_read_b128 v[148:151], v156 offset:1024
	ds_read_b128 v[152:155], v156 offset:2048
	ds_read_b128 v[156:159], v156 offset:3072
	ds_read_b128 v[160:163], v172
	ds_read_b128 v[164:167], v172 offset:1024
	ds_read_b128 v[168:171], v172 offset:2048
	ds_read_b128 v[172:175], v172 offset:3072
	s_add_u32 s18, s24, 0x80000
	s_addc_u32 s19, s25, 0
	s_mov_b32 m0, s11
	v_lshl_add_u64 v[234:235], s[18:19], 0, v[132:133]
	ds_read_b128 v[176:179], v143 offset:32768
	ds_read_b128 v[180:183], v143 offset:33792
	ds_read_b128 v[184:187], v143 offset:34816
	ds_read_b128 v[188:191], v143 offset:35840
	ds_read_b128 v[204:207], v143 offset:36864
	ds_read_b128 v[220:223], v143 offset:37888
	ds_read_b128 v[224:227], v143 offset:38912
	ds_read_b128 v[228:231], v143 offset:39936
	global_load_lds_dwordx4 v[234:235], off
	v_lshl_add_u64 v[234:235], s[18:19], 0, v[134:135]
	s_mov_b32 m0, s27
	s_nop 0
	global_load_lds_dwordx4 v[234:235], off
	s_waitcnt vmcnt(8)
	s_waitcnt lgkmcnt(0)
	s_setprio 1
	s_barrier
	v_mfma_f32_16x16x32_bf16 v[58:61], v[144:147], v[176:179], v[58:61]
	v_mfma_f32_16x16x32_bf16 v[62:65], v[152:155], v[176:179], v[62:65]
	v_mfma_f32_16x16x32_bf16 v[42:45], v[144:147], v[184:187], v[42:45]
	v_mfma_f32_16x16x32_bf16 v[46:49], v[152:155], v[184:187], v[46:49]
	v_mfma_f32_16x16x32_bf16 v[26:29], v[144:147], v[204:207], v[26:29]
	v_mfma_f32_16x16x32_bf16 v[30:33], v[152:155], v[204:207], v[30:33]
	v_mfma_f32_16x16x32_bf16 v[10:13], v[144:147], v[224:227], v[10:13]
	v_mfma_f32_16x16x32_bf16 v[14:17], v[152:155], v[224:227], v[14:17]
	v_mfma_f32_16x16x32_bf16 v[58:61], v[148:151], v[180:183], v[58:61]
	v_mfma_f32_16x16x32_bf16 v[62:65], v[156:159], v[180:183], v[62:65]
	v_mfma_f32_16x16x32_bf16 v[42:45], v[148:151], v[188:191], v[42:45]
	v_mfma_f32_16x16x32_bf16 v[46:49], v[156:159], v[188:191], v[46:49]
	v_mfma_f32_16x16x32_bf16 v[26:29], v[148:151], v[220:223], v[26:29]
	v_mfma_f32_16x16x32_bf16 v[30:33], v[156:159], v[220:223], v[30:33]
	v_mfma_f32_16x16x32_bf16 v[10:13], v[148:151], v[228:231], v[10:13]
	v_mfma_f32_16x16x32_bf16 v[14:17], v[156:159], v[228:231], v[14:17]
	s_setprio 0
	s_setprio 1
	v_mfma_f32_16x16x32_bf16 v[50:53], v[160:163], v[176:179], v[50:53]
	v_mfma_f32_16x16x32_bf16 v[54:57], v[168:171], v[176:179], v[54:57]
	v_mfma_f32_16x16x32_bf16 v[34:37], v[160:163], v[184:187], v[34:37]
	v_mfma_f32_16x16x32_bf16 v[38:41], v[168:171], v[184:187], v[38:41]
	v_mfma_f32_16x16x32_bf16 v[18:21], v[160:163], v[204:207], v[18:21]
	v_mfma_f32_16x16x32_bf16 v[22:25], v[168:171], v[204:207], v[22:25]
	v_mfma_f32_16x16x32_bf16 v[2:5], v[160:163], v[224:227], v[2:5]
	v_mfma_f32_16x16x32_bf16 v[6:9], v[168:171], v[224:227], v[6:9]
	v_mfma_f32_16x16x32_bf16 v[50:53], v[164:167], v[180:183], v[50:53]
	v_mfma_f32_16x16x32_bf16 v[54:57], v[172:175], v[180:183], v[54:57]
	v_mfma_f32_16x16x32_bf16 v[34:37], v[164:167], v[188:191], v[34:37]
	v_mfma_f32_16x16x32_bf16 v[38:41], v[172:175], v[188:191], v[38:41]
	v_mfma_f32_16x16x32_bf16 v[18:21], v[164:167], v[220:223], v[18:21]
	v_mfma_f32_16x16x32_bf16 v[22:25], v[172:175], v[220:223], v[22:25]
	v_mfma_f32_16x16x32_bf16 v[2:5], v[164:167], v[228:231], v[2:5]
	v_mfma_f32_16x16x32_bf16 v[6:9], v[172:175], v[228:231], v[6:9]
	s_barrier
; #define PG8_STAGE(bufoff, gbase, voff) do { _Pragma("unroll") for (int _i = 0; _i < 2; ++_i) \
;         __builtin_amdgcn_global_load_lds((const unsigned*)((const char*)(gbase) + (voff)[_i]), (PG8_LAS unsigned*)(lds + (bufoff) + ldsw + _i * 8192), 16, 0, 0); } while (0)
; #define PG8_LDA(dst, b, h) do { _Pragma("unroll") for (int m = 0; m < 4; ++m) _Pragma("unroll") for (int k = 0; k < 2; ++k) dst[m][k] = *(const PG8_LAS bf16x8*)(lds + PG8_SA(b, h) + aoff + m * 2048 + k * 1024); } while (0)
; #define PG8_MMA(ai, bj, At, Bt) do { __builtin_amdgcn_s_setprio(1); _Pragma("unroll") for (int m = 0; m < 4; ++m) _Pragma("unroll") for (int n = 0; n < 2; ++n) _Pragma("unroll") for (int k = 0; k < 2; ++k) \
;         acc[ai][bj][m][n] = __builtin_amdgcn_mfma_f32_16x16x32_bf16(Bt[n][k], At[m][k], acc[ai][bj][m][n], 0, 0, 0); __builtin_amdgcn_s_setprio(0); } while (0)
; #define PG8_WAIT_V(n) asm volatile("s_waitcnt vmcnt(" #n ")" ::: "memory")
; #define PG8_WAIT_L(n) asm volatile("s_waitcnt lgkmcnt(" #n ")" ::: "memory")
; #define PG8_BAR __builtin_amdgcn_s_barrier()
; #define PG8_SCHED __builtin_amdgcn_sched_barrier(0)
; template <class Epi, class Sched, bool ALIGN_EPI = false, bool SP2 = false>
; __device__ __forceinline__ void gemm_phase(PG8_LAS unsigned char* lds, const Gemm g, const Sched& S, const Epi& E) {
;     ...
;         for (int t = 0; t < nt; t += 2) {
;             const bool last = (t == nt - 2);
;             const char* a1 = cA + (size_t)(t + 1) * kstep;
;             const char* a2 = last ? nA : cA + (size_t)(t + 2) * kstep; const char* b2 = last ? nB : cB + (size_t)(t + 2) * kstep;
;     ...
;             PG8_LDA(At, 1, 1); PG8_STAGE(PG8_SB(1, 0), b3, voffB); PG8_STAGE(PG8_SB(1, 1), b3 + hstep, voffB); PG8_STAGE(PG8_SA(1, 0), a3, voffA);
;             PG8_WAIT_V(8); PG8_WAIT_L(0); PG8_BAR; PG8_MMA(1, 0, At, B0); PG8_MMA(1, 1, At, B1); PG8_BAR; PG8_SCHED;
	s_setprio 0
	s_add_i32 s18, s39, s3
	v_lshl_add_u64 v[192:193], v[192:193], 0, s[56:57]
	s_mov_b32 m0, s18
	ds_read_b128 v[176:179], v143 offset:49152
	ds_read_b128 v[180:183], v143 offset:50176
	ds_read_b128 v[184:187], v143 offset:51200
	ds_read_b128 v[188:191], v143 offset:52224
	ds_read_b128 v[204:207], v143 offset:53248
	ds_read_b128 v[220:223], v143 offset:54272
	ds_read_b128 v[224:227], v143 offset:55296
	ds_read_b128 v[228:231], v143 offset:56320
	global_load_lds_dwordx4 v[192:193], off
	s_add_i32 m0, s18, 0x2000
	s_add_u32 s18, s22, 0x80080
	v_lshl_add_u64 v[192:193], v[200:201], 0, s[56:57]
	s_addc_u32 s19, s23, 0
	s_add_i32 s22, s40, s3
	global_load_lds_dwordx4 v[192:193], off
	v_lshl_add_u64 v[192:193], s[18:19], 0, v[0:1]
	s_mov_b32 m0, s22
	s_nop 0
	global_load_lds_dwordx4 v[192:193], off
	v_lshl_add_u64 v[192:193], s[18:19], 0, v[136:137]
	s_add_i32 m0, s22, 0x2000
	s_nop 0
	global_load_lds_dwordx4 v[192:193], off
	v_lshl_add_u64 v[192:193], v[202:203], 0, s[56:57]
	s_mov_b32 m0, s33
	s_nop 0
	global_load_lds_dwordx4 v[192:193], off
	v_lshl_add_u64 v[192:193], v[232:233], 0, s[56:57]
	s_mov_b32 m0, s37
	s_nop 0
	global_load_lds_dwordx4 v[192:193], off
	s_waitcnt vmcnt(8)
	s_waitcnt lgkmcnt(0)
	s_setprio 1
	s_barrier
	v_mfma_f32_16x16x32_bf16 v[90:93], v[144:147], v[176:179], v[90:93]
	v_mfma_f32_16x16x32_bf16 v[94:97], v[152:155], v[176:179], v[94:97]
	v_mfma_f32_16x16x32_bf16 v[74:77], v[144:147], v[184:187], v[74:77]
	v_mfma_f32_16x16x32_bf16 v[78:81], v[152:155], v[184:187], v[78:81]
	v_mfma_f32_16x16x32_bf16 v[122:125], v[144:147], v[204:207], v[122:125]
	v_mfma_f32_16x16x32_bf16 v[126:129], v[152:155], v[204:207], v[126:129]
	v_mfma_f32_16x16x32_bf16 v[106:109], v[144:147], v[224:227], v[106:109]
	v_mfma_f32_16x16x32_bf16 v[110:113], v[152:155], v[224:227], v[110:113]
	v_mfma_f32_16x16x32_bf16 v[90:93], v[148:151], v[180:183], v[90:93]
	v_mfma_f32_16x16x32_bf16 v[94:97], v[156:159], v[180:183], v[94:97]
	v_mfma_f32_16x16x32_bf16 v[74:77], v[148:151], v[188:191], v[74:77]
	v_mfma_f32_16x16x32_bf16 v[78:81], v[156:159], v[188:191], v[78:81]
	v_mfma_f32_16x16x32_bf16 v[122:125], v[148:151], v[220:223], v[122:125]
	v_mfma_f32_16x16x32_bf16 v[126:129], v[156:159], v[220:223], v[126:129]
	v_mfma_f32_16x16x32_bf16 v[106:109], v[148:151], v[228:231], v[106:109]
	v_mfma_f32_16x16x32_bf16 v[110:113], v[156:159], v[228:231], v[110:113]
	s_setprio 0
	s_setprio 1
	v_mfma_f32_16x16x32_bf16 v[82:85], v[160:163], v[176:179], v[82:85]
	v_mfma_f32_16x16x32_bf16 v[86:89], v[168:171], v[176:179], v[86:89]
	v_mfma_f32_16x16x32_bf16 v[66:69], v[160:163], v[184:187], v[66:69]
	v_mfma_f32_16x16x32_bf16 v[70:73], v[168:171], v[184:187], v[70:73]
	v_mfma_f32_16x16x32_bf16 v[114:117], v[160:163], v[204:207], v[114:117]
	v_mfma_f32_16x16x32_bf16 v[118:121], v[168:171], v[204:207], v[118:121]
	v_mfma_f32_16x16x32_bf16 v[102:105], v[160:163], v[224:227], v[102:105]
	v_mfma_f32_16x16x32_bf16 v[98:101], v[168:171], v[224:227], v[98:101]
	v_mfma_f32_16x16x32_bf16 v[82:85], v[164:167], v[180:183], v[82:85]
	v_mfma_f32_16x16x32_bf16 v[86:89], v[172:175], v[180:183], v[86:89]
	v_mfma_f32_16x16x32_bf16 v[66:69], v[164:167], v[188:191], v[66:69]
	v_mfma_f32_16x16x32_bf16 v[70:73], v[172:175], v[188:191], v[70:73]
	v_mfma_f32_16x16x32_bf16 v[114:117], v[164:167], v[220:223], v[114:117]
	v_mfma_f32_16x16x32_bf16 v[118:121], v[172:175], v[220:223], v[118:121]
	v_mfma_f32_16x16x32_bf16 v[102:105], v[164:167], v[228:231], v[102:105]
	v_mfma_f32_16x16x32_bf16 v[98:101], v[172:175], v[228:231], v[98:101]
	s_barrier
	s_setprio 0
	s_add_i32 s38, s38, 2
	s_cmp_gt_u32 s38, 5
	s_mov_b64 s[18:19], s[20:21]
	s_cbranch_scc0 .LBB0_516
	s_cmpk_lt_u32 s2, 0x100
	s_cbranch_scc0 .LBB0_519
	s_barrier

; #define PG8_STAGE(bufoff, gbase, voff) do { _Pragma("unroll") for (int _i = 0; _i < 2; ++_i) \
;         __builtin_amdgcn_global_load_lds((const unsigned*)((const char*)(gbase) + (voff)[_i]), (PG8_LAS unsigned*)(lds + (bufoff) + ldsw + _i * 8192), 16, 0, 0); } while (0)
; #define PG8_LDA(dst, b, h) do { _Pragma("unroll") for (int m = 0; m < 4; ++m) _Pragma("unroll") for (int k = 0; k < 2; ++k) dst[m][k] = *(const PG8_LAS bf16x8*)(lds + PG8_SA(b, h) + aoff + m * 2048 + k * 1024); } while (0)
; #define PG8_LDB(dst, b, h) do { _Pragma("unroll") for (int n = 0; n < 2; ++n) _Pragma("unroll") for (int k = 0; k < 2; ++k) dst[n][k] = *(const PG8_LAS bf16x8*)(lds + PG8_SB(b, h) + boff + n * 2048 + k * 1024); } while (0)
; #define PG8_MMA(ai, bj, At, Bt) do { __builtin_amdgcn_s_setprio(1); _Pragma("unroll") for (int m = 0; m < 4; ++m) _Pragma("unroll") for (int n = 0; n < 2; ++n) _Pragma("unroll") for (int k = 0; k < 2; ++k) \
;         acc[ai][bj][m][n] = __builtin_amdgcn_mfma_f32_16x16x32_bf16(Bt[n][k], At[m][k], acc[ai][bj][m][n], 0, 0, 0); __builtin_amdgcn_s_setprio(0); } while (0)
; #define PG8_WAIT_V(n) asm volatile("s_waitcnt vmcnt(" #n ")" ::: "memory")
; #define PG8_WAIT_L(n) asm volatile("s_waitcnt lgkmcnt(" #n ")" ::: "memory")
; template <class Epi, class Sched, bool ALIGN_EPI = false, bool SP2 = false>
; __device__ __forceinline__ void gemm_phase(PG8_LAS unsigned char* lds, const Gemm g, const Sched& S, const Epi& E) {
;     ...
;             const bool last = (t == nt - 2);
;             const char* a1 = cA + (size_t)(t + 1) * kstep;
;             const char* a2 = last ? nA : cA + (size_t)(t + 2) * kstep; const char* b2 = last ? nB : cB + (size_t)(t + 2) * kstep;
;             const char* a3 = a2 + kstep; const char* b3 = b2 + kstep;
;             if (last && has_next) S.a_ready(nxt);
;             if constexpr (SP2) {
;             PG8_LDB(B0, 0, 0); PG8_LDB(B1, 0, 1); PG8_SCHED; PG8_LDA(At, 0, 0); PG8_STAGE(PG8_SA(1, 1), a1 + hstep, voffA);
;             PG8_WAIT_V(8); PG8_WAIT_L(0); PG8_BAR; PG8_MMA(0, 0, At, B0); PG8_MMA(0, 1, At, B1); PG8_BAR; PG8_SCHED;
;             PG8_LDA(At, 0, 1); PG8_STAGE(PG8_SB(0, 0), b2, voffB); PG8_STAGE(PG8_SB(0, 1), b2 + hstep, voffB); PG8_STAGE(PG8_SA(0, 0), a2, voffA);
;             PG8_WAIT_V(8); PG8_WAIT_L(0); PG8_BAR; PG8_MMA(1, 0, At, B0); PG8_MMA(1, 1, At, B1); PG8_BAR; PG8_SCHED;
.LBB0_643:
	s_add_u32 s44, s24, 0xfff80080
	s_addc_u32 s45, s25, -1
	s_add_i32 s74, 0, 0x10000
	s_cmp_eq_u32 s51, 28
	s_cselect_b32 s49, s21, s45
	s_cselect_b32 s48, s20, s44
	v_add_u32_e32 v0, s74, v192
	s_cselect_b32 s45, s19, s47
	s_cselect_b32 s44, s26, s27
	s_add_i32 s73, 0, 0x14000
	ds_read_b128 v[130:133], v0
	ds_read_b128 v[134:137], v0 offset:1024
	ds_read_b128 v[138:141], v0 offset:2048
	ds_read_b128 v[142:145], v0 offset:3072
	v_add_u32_e32 v0, s73, v192
	ds_read_b128 v[146:149], v0
	ds_read_b128 v[150:153], v0 offset:1024
	ds_read_b128 v[168:171], v0 offset:2048
	ds_read_b128 v[172:175], v0 offset:3072
	v_lshl_add_u64 v[154:155], s[24:25], 0, v[164:165]
	s_add_i32 m0, s77, 0xc000
	ds_read_b128 v[176:179], v193
	ds_read_b128 v[180:183], v193 offset:1024
	ds_read_b128 v[186:189], v193 offset:2048
	ds_read_b128 v[204:207], v193 offset:3072
	ds_read_b128 v[218:221], v193 offset:4096
	ds_read_b128 v[222:225], v193 offset:5120
	ds_read_b128 v[226:229], v193 offset:6144
	ds_read_b128 v[230:233], v193 offset:7168
	global_load_lds_dwordx4 v[154:155], off
	v_lshl_add_u64 v[154:155], s[24:25], 0, v[166:167]
	s_add_i32 m0, s77, 0xe000
	s_nop 0
	global_load_lds_dwordx4 v[154:155], off
	s_waitcnt vmcnt(8)
	s_waitcnt lgkmcnt(0)
	s_setprio 1
	s_barrier
	v_mfma_f32_16x16x32_bf16 v[126:129], v[130:133], v[176:179], v[126:129]
	v_mfma_f32_16x16x32_bf16 v[122:125], v[138:141], v[176:179], v[122:125]
	v_mfma_f32_16x16x32_bf16 v[110:113], v[130:133], v[186:189], v[110:113]
	v_mfma_f32_16x16x32_bf16 v[106:109], v[138:141], v[186:189], v[106:109]
	v_mfma_f32_16x16x32_bf16 v[94:97], v[130:133], v[218:221], v[94:97]
	v_mfma_f32_16x16x32_bf16 v[90:93], v[138:141], v[218:221], v[90:93]
	v_mfma_f32_16x16x32_bf16 v[78:81], v[130:133], v[226:229], v[78:81]
	v_mfma_f32_16x16x32_bf16 v[74:77], v[138:141], v[226:229], v[74:77]
	v_mfma_f32_16x16x32_bf16 v[126:129], v[134:137], v[180:183], v[126:129]
	v_mfma_f32_16x16x32_bf16 v[122:125], v[142:145], v[180:183], v[122:125]
	v_mfma_f32_16x16x32_bf16 v[110:113], v[134:137], v[204:207], v[110:113]
	v_mfma_f32_16x16x32_bf16 v[106:109], v[142:145], v[204:207], v[106:109]
	v_mfma_f32_16x16x32_bf16 v[94:97], v[134:137], v[222:225], v[94:97]
	v_mfma_f32_16x16x32_bf16 v[90:93], v[142:145], v[222:225], v[90:93]
	v_mfma_f32_16x16x32_bf16 v[78:81], v[134:137], v[230:233], v[78:81]
	v_mfma_f32_16x16x32_bf16 v[74:77], v[142:145], v[230:233], v[74:77]
	s_setprio 0
	s_setprio 1
	v_mfma_f32_16x16x32_bf16 v[114:117], v[146:149], v[176:179], v[114:117]
	v_mfma_f32_16x16x32_bf16 v[118:121], v[168:171], v[176:179], v[118:121]
	v_mfma_f32_16x16x32_bf16 v[98:101], v[146:149], v[186:189], v[98:101]
	v_mfma_f32_16x16x32_bf16 v[102:105], v[168:171], v[186:189], v[102:105]
	v_mfma_f32_16x16x32_bf16 v[82:85], v[146:149], v[218:221], v[82:85]
	v_mfma_f32_16x16x32_bf16 v[86:89], v[168:171], v[218:221], v[86:89]
	v_mfma_f32_16x16x32_bf16 v[66:69], v[146:149], v[226:229], v[66:69]
	v_mfma_f32_16x16x32_bf16 v[70:73], v[168:171], v[226:229], v[70:73]
	v_mfma_f32_16x16x32_bf16 v[114:117], v[150:153], v[180:183], v[114:117]
	v_mfma_f32_16x16x32_bf16 v[118:121], v[172:175], v[180:183], v[118:121]
	v_mfma_f32_16x16x32_bf16 v[98:101], v[150:153], v[204:207], v[98:101]
	v_mfma_f32_16x16x32_bf16 v[102:105], v[172:175], v[204:207], v[102:105]
	v_mfma_f32_16x16x32_bf16 v[82:85], v[150:153], v[222:225], v[82:85]
	v_mfma_f32_16x16x32_bf16 v[86:89], v[172:175], v[222:225], v[86:89]
	v_mfma_f32_16x16x32_bf16 v[66:69], v[150:153], v[230:233], v[66:69]
	v_mfma_f32_16x16x32_bf16 v[70:73], v[172:175], v[230:233], v[70:73]
	s_barrier
	s_setprio 0
	s_add_i32 s74, s74, s76
	v_lshl_add_u64 v[154:155], s[44:45], 0, v[158:159]
	s_mov_b32 m0, s74
	ds_read_b128 v[176:179], v193 offset:16384
	ds_read_b128 v[180:183], v193 offset:17408
	ds_read_b128 v[186:189], v193 offset:18432
	ds_read_b128 v[204:207], v193 offset:19456
	ds_read_b128 v[218:221], v193 offset:20480
	ds_read_b128 v[222:225], v193 offset:21504
	ds_read_b128 v[226:229], v193 offset:22528
	ds_read_b128 v[230:233], v193 offset:23552
	global_load_lds_dwordx4 v[154:155], off
	s_add_i32 m0, s74, 0x2000
	s_add_u32 vcc_lo, s44, 0x80000
	v_lshl_add_u64 v[200:201], s[44:45], 0, v[162:163]
	s_addc_u32 vcc_hi, s45, 0
	s_add_i32 s73, s73, s76
	global_load_lds_dwordx4 v[200:201], off
	v_lshl_add_u64 v[202:203], vcc, 0, v[158:159]
	s_mov_b32 m0, s73
	v_lshl_add_u64 v[234:235], s[48:49], 0, v[160:161]
	global_load_lds_dwordx4 v[202:203], off
	v_lshl_add_u64 v[202:203], vcc, 0, v[162:163]
	s_add_i32 m0, s73, 0x2000
	s_nop 0
	global_load_lds_dwordx4 v[202:203], off
	v_lshl_add_u64 v[202:203], s[48:49], 0, v[156:157]
	s_mov_b32 m0, s77
	s_nop 0
	global_load_lds_dwordx4 v[202:203], off
	s_mov_b32 m0, s78
	s_nop 0
	global_load_lds_dwordx4 v[234:235], off
	s_waitcnt vmcnt(8)
	s_waitcnt lgkmcnt(0)
	s_setprio 1
	s_barrier
; #define PG8_STAGE(bufoff, gbase, voff) do { _Pragma("unroll") for (int _i = 0; _i < 2; ++_i) \
;         __builtin_amdgcn_global_load_lds((const unsigned*)((const char*)(gbase) + (voff)[_i]), (PG8_LAS unsigned*)(lds + (bufoff) + ldsw + _i * 8192), 16, 0, 0); } while (0)
; #define PG8_LDA(dst, b, h) do { _Pragma("unroll") for (int m = 0; m < 4; ++m) _Pragma("unroll") for (int k = 0; k < 2; ++k) dst[m][k] = *(const PG8_LAS bf16x8*)(lds + PG8_SA(b, h) + aoff + m * 2048 + k * 1024); } while (0)
; #define PG8_LDB(dst, b, h) do { _Pragma("unroll") for (int n = 0; n < 2; ++n) _Pragma("unroll") for (int k = 0; k < 2; ++k) dst[n][k] = *(const PG8_LAS bf16x8*)(lds + PG8_SB(b, h) + boff + n * 2048 + k * 1024); } while (0)
; #define PG8_MMA(ai, bj, At, Bt) do { __builtin_amdgcn_s_setprio(1); _Pragma("unroll") for (int m = 0; m < 4; ++m) _Pragma("unroll") for (int n = 0; n < 2; ++n) _Pragma("unroll") for (int k = 0; k < 2; ++k) \
;         acc[ai][bj][m][n] = __builtin_amdgcn_mfma_f32_16x16x32_bf16(Bt[n][k], At[m][k], acc[ai][bj][m][n], 0, 0, 0); __builtin_amdgcn_s_setprio(0); } while (0)
; #define PG8_WAIT_V(n) asm volatile("s_waitcnt vmcnt(" #n ")" ::: "memory")
; #define PG8_WAIT_L(n) asm volatile("s_waitcnt lgkmcnt(" #n ")" ::: "memory")
; #define PG8_BAR __builtin_amdgcn_s_barrier()
; #define PG8_SCHED __builtin_amdgcn_sched_barrier(0)
; template <class Epi, class Sched, bool ALIGN_EPI = false, bool SP2 = false>
; __device__ __forceinline__ void gemm_phase(PG8_LAS unsigned char* lds, const Gemm g, const Sched& S, const Epi& E) {
;     ...
;             PG8_WAIT_V(8); PG8_WAIT_L(0); PG8_BAR; PG8_MMA(1, 0, At, B0); PG8_MMA(1, 1, At, B1); PG8_BAR; PG8_SCHED;
;             PG8_LDB(B0, 1, 0); PG8_LDB(B1, 1, 1); PG8_SCHED; PG8_LDA(At, 1, 0); PG8_STAGE(PG8_SA(0, 1), a2 + hstep, voffA);
;             PG8_WAIT_V(8); PG8_WAIT_L(0); PG8_BAR; PG8_MMA(0, 0, At, B0); PG8_MMA(0, 1, At, B1); PG8_BAR; PG8_SCHED;
	v_mfma_f32_16x16x32_bf16 v[62:65], v[130:133], v[176:179], v[62:65]
	v_mfma_f32_16x16x32_bf16 v[58:61], v[138:141], v[176:179], v[58:61]
	v_mfma_f32_16x16x32_bf16 v[46:49], v[130:133], v[186:189], v[46:49]
	v_mfma_f32_16x16x32_bf16 v[42:45], v[138:141], v[186:189], v[42:45]
	v_mfma_f32_16x16x32_bf16 v[30:33], v[130:133], v[218:221], v[30:33]
	v_mfma_f32_16x16x32_bf16 v[26:29], v[138:141], v[218:221], v[26:29]
	v_mfma_f32_16x16x32_bf16 v[14:17], v[130:133], v[226:229], v[14:17]
	v_mfma_f32_16x16x32_bf16 v[10:13], v[138:141], v[226:229], v[10:13]
	v_mfma_f32_16x16x32_bf16 v[62:65], v[134:137], v[180:183], v[62:65]
	v_mfma_f32_16x16x32_bf16 v[58:61], v[142:145], v[180:183], v[58:61]
	v_mfma_f32_16x16x32_bf16 v[46:49], v[134:137], v[204:207], v[46:49]
	v_mfma_f32_16x16x32_bf16 v[42:45], v[142:145], v[204:207], v[42:45]
	v_mfma_f32_16x16x32_bf16 v[30:33], v[134:137], v[222:225], v[30:33]
	v_mfma_f32_16x16x32_bf16 v[26:29], v[142:145], v[222:225], v[26:29]
	v_mfma_f32_16x16x32_bf16 v[14:17], v[134:137], v[230:233], v[14:17]
	v_mfma_f32_16x16x32_bf16 v[10:13], v[142:145], v[230:233], v[10:13]
	s_setprio 0
	s_setprio 1
	v_mfma_f32_16x16x32_bf16 v[50:53], v[146:149], v[176:179], v[50:53]
	v_mfma_f32_16x16x32_bf16 v[54:57], v[168:171], v[176:179], v[54:57]
	v_mfma_f32_16x16x32_bf16 v[34:37], v[146:149], v[186:189], v[34:37]
	v_mfma_f32_16x16x32_bf16 v[38:41], v[168:171], v[186:189], v[38:41]
	v_mfma_f32_16x16x32_bf16 v[18:21], v[146:149], v[218:221], v[18:21]
	v_mfma_f32_16x16x32_bf16 v[22:25], v[168:171], v[218:221], v[22:25]
	v_mfma_f32_16x16x32_bf16 v[2:5], v[146:149], v[226:229], v[2:5]
	v_mfma_f32_16x16x32_bf16 v[6:9], v[168:171], v[226:229], v[6:9]
	v_mfma_f32_16x16x32_bf16 v[50:53], v[150:153], v[180:183], v[50:53]
	v_mfma_f32_16x16x32_bf16 v[54:57], v[172:175], v[180:183], v[54:57]
	v_mfma_f32_16x16x32_bf16 v[34:37], v[150:153], v[204:207], v[34:37]
	v_mfma_f32_16x16x32_bf16 v[38:41], v[172:175], v[204:207], v[38:41]
	v_mfma_f32_16x16x32_bf16 v[18:21], v[150:153], v[222:225], v[18:21]
	v_mfma_f32_16x16x32_bf16 v[22:25], v[172:175], v[222:225], v[22:25]
	v_mfma_f32_16x16x32_bf16 v[2:5], v[150:153], v[230:233], v[2:5]
	v_mfma_f32_16x16x32_bf16 v[6:9], v[172:175], v[230:233], v[6:9]
	s_barrier
	s_setprio 0
	s_add_i32 s73, 0, 0x18000
	v_add_u32_e32 v0, s73, v192
	s_add_i32 s74, 0, 0x1c000
	ds_read_b128 v[130:133], v0
	ds_read_b128 v[134:137], v0 offset:1024
	ds_read_b128 v[138:141], v0 offset:2048
	ds_read_b128 v[142:145], v0 offset:3072
	v_add_u32_e32 v0, s74, v192
	ds_read_b128 v[146:149], v0
	ds_read_b128 v[150:153], v0 offset:1024
	ds_read_b128 v[168:171], v0 offset:2048
	ds_read_b128 v[172:175], v0 offset:3072
	s_add_u32 s48, s48, 0x80000
	s_addc_u32 s49, s49, 0
	s_mov_b32 m0, s79
	v_lshl_add_u64 v[236:237], s[48:49], 0, v[156:157]
	ds_read_b128 v[176:179], v193 offset:32768
	ds_read_b128 v[180:183], v193 offset:33792
	ds_read_b128 v[186:189], v193 offset:34816
	ds_read_b128 v[204:207], v193 offset:35840
	ds_read_b128 v[218:221], v193 offset:36864
	ds_read_b128 v[222:225], v193 offset:37888
	ds_read_b128 v[226:229], v193 offset:38912
	ds_read_b128 v[230:233], v193 offset:39936
	global_load_lds_dwordx4 v[236:237], off
	v_lshl_add_u64 v[236:237], s[48:49], 0, v[160:161]
	s_mov_b32 m0, s80
	s_nop 0
	global_load_lds_dwordx4 v[236:237], off
	s_waitcnt vmcnt(8)
	s_waitcnt lgkmcnt(0)
	s_setprio 1
	s_barrier
	v_mfma_f32_16x16x32_bf16 v[126:129], v[130:133], v[176:179], v[126:129]
	v_mfma_f32_16x16x32_bf16 v[122:125], v[138:141], v[176:179], v[122:125]
	v_mfma_f32_16x16x32_bf16 v[110:113], v[130:133], v[186:189], v[110:113]
	v_mfma_f32_16x16x32_bf16 v[106:109], v[138:141], v[186:189], v[106:109]
	v_mfma_f32_16x16x32_bf16 v[94:97], v[130:133], v[218:221], v[94:97]
	v_mfma_f32_16x16x32_bf16 v[90:93], v[138:141], v[218:221], v[90:93]
	v_mfma_f32_16x16x32_bf16 v[78:81], v[130:133], v[226:229], v[78:81]
	v_mfma_f32_16x16x32_bf16 v[74:77], v[138:141], v[226:229], v[74:77]
	v_mfma_f32_16x16x32_bf16 v[126:129], v[134:137], v[180:183], v[126:129]
	v_mfma_f32_16x16x32_bf16 v[122:125], v[142:145], v[180:183], v[122:125]
	v_mfma_f32_16x16x32_bf16 v[110:113], v[134:137], v[204:207], v[110:113]
	v_mfma_f32_16x16x32_bf16 v[106:109], v[142:145], v[204:207], v[106:109]
	v_mfma_f32_16x16x32_bf16 v[94:97], v[134:137], v[222:225], v[94:97]
	v_mfma_f32_16x16x32_bf16 v[90:93], v[142:145], v[222:225], v[90:93]
	v_mfma_f32_16x16x32_bf16 v[78:81], v[134:137], v[230:233], v[78:81]
	v_mfma_f32_16x16x32_bf16 v[74:77], v[142:145], v[230:233], v[74:77]
	s_setprio 0
	s_setprio 1
	v_mfma_f32_16x16x32_bf16 v[114:117], v[146:149], v[176:179], v[114:117]
	v_mfma_f32_16x16x32_bf16 v[118:121], v[168:171], v[176:179], v[118:121]
	v_mfma_f32_16x16x32_bf16 v[98:101], v[146:149], v[186:189], v[98:101]
	v_mfma_f32_16x16x32_bf16 v[102:105], v[168:171], v[186:189], v[102:105]
	v_mfma_f32_16x16x32_bf16 v[82:85], v[146:149], v[218:221], v[82:85]
	v_mfma_f32_16x16x32_bf16 v[86:89], v[168:171], v[218:221], v[86:89]
	v_mfma_f32_16x16x32_bf16 v[66:69], v[146:149], v[226:229], v[66:69]
	v_mfma_f32_16x16x32_bf16 v[70:73], v[168:171], v[226:229], v[70:73]
	v_mfma_f32_16x16x32_bf16 v[114:117], v[150:153], v[180:183], v[114:117]
	v_mfma_f32_16x16x32_bf16 v[118:121], v[172:175], v[180:183], v[118:121]
	v_mfma_f32_16x16x32_bf16 v[98:101], v[150:153], v[204:207], v[98:101]
	v_mfma_f32_16x16x32_bf16 v[102:105], v[172:175], v[204:207], v[102:105]
	v_mfma_f32_16x16x32_bf16 v[82:85], v[150:153], v[222:225], v[82:85]
	v_mfma_f32_16x16x32_bf16 v[86:89], v[172:175], v[222:225], v[86:89]
	v_mfma_f32_16x16x32_bf16 v[66:69], v[150:153], v[230:233], v[66:69]
	v_mfma_f32_16x16x32_bf16 v[70:73], v[172:175], v[230:233], v[70:73]
	s_barrier
; #define PG8_STAGE(bufoff, gbase, voff) do { _Pragma("unroll") for (int _i = 0; _i < 2; ++_i) \
;         __builtin_amdgcn_global_load_lds((const unsigned*)((const char*)(gbase) + (voff)[_i]), (PG8_LAS unsigned*)(lds + (bufoff) + ldsw + _i * 8192), 16, 0, 0); } while (0)
; #define PG8_LDA(dst, b, h) do { _Pragma("unroll") for (int m = 0; m < 4; ++m) _Pragma("unroll") for (int k = 0; k < 2; ++k) dst[m][k] = *(const PG8_LAS bf16x8*)(lds + PG8_SA(b, h) + aoff + m * 2048 + k * 1024); } while (0)
; #define PG8_MMA(ai, bj, At, Bt) do { __builtin_amdgcn_s_setprio(1); _Pragma("unroll") for (int m = 0; m < 4; ++m) _Pragma("unroll") for (int n = 0; n < 2; ++n) _Pragma("unroll") for (int k = 0; k < 2; ++k) \
;         acc[ai][bj][m][n] = __builtin_amdgcn_mfma_f32_16x16x32_bf16(Bt[n][k], At[m][k], acc[ai][bj][m][n], 0, 0, 0); __builtin_amdgcn_s_setprio(0); } while (0)
; #define PG8_WAIT_V(n) asm volatile("s_waitcnt vmcnt(" #n ")" ::: "memory")
; #define PG8_WAIT_L(n) asm volatile("s_waitcnt lgkmcnt(" #n ")" ::: "memory")
; #define PG8_BAR __builtin_amdgcn_s_barrier()
; #define PG8_SCHED __builtin_amdgcn_sched_barrier(0)
; template <class Epi, class Sched, bool ALIGN_EPI = false, bool SP2 = false>
; __device__ __forceinline__ void gemm_phase(PG8_LAS unsigned char* lds, const Gemm g, const Sched& S, const Epi& E) {
;     ...
;         for (int t = 0; t < nt; t += 2) {
;             const bool last = (t == nt - 2);
;             const char* a1 = cA + (size_t)(t + 1) * kstep;
;             const char* a2 = last ? nA : cA + (size_t)(t + 2) * kstep; const char* b2 = last ? nB : cB + (size_t)(t + 2) * kstep;
;     ...
;             PG8_LDA(At, 1, 1); PG8_STAGE(PG8_SB(1, 0), b3, voffB); PG8_STAGE(PG8_SB(1, 1), b3 + hstep, voffB); PG8_STAGE(PG8_SA(1, 0), a3, voffA);
;             PG8_WAIT_V(8); PG8_WAIT_L(0); PG8_BAR; PG8_MMA(1, 0, At, B0); PG8_MMA(1, 1, At, B1); PG8_BAR; PG8_SCHED;
	s_setprio 0
	s_add_i32 s48, s73, s76
	v_lshl_add_u64 v[154:155], v[154:155], 0, s[56:57]
	s_mov_b32 m0, s48
	ds_read_b128 v[176:179], v193 offset:49152
	ds_read_b128 v[180:183], v193 offset:50176
	ds_read_b128 v[186:189], v193 offset:51200
	ds_read_b128 v[204:207], v193 offset:52224
	ds_read_b128 v[218:221], v193 offset:53248
	ds_read_b128 v[222:225], v193 offset:54272
	ds_read_b128 v[226:229], v193 offset:55296
	ds_read_b128 v[230:233], v193 offset:56320
	global_load_lds_dwordx4 v[154:155], off
	s_add_i32 m0, s48, 0x2000
	s_add_u32 s44, s44, 0x80080
	v_lshl_add_u64 v[154:155], v[200:201], 0, s[56:57]
	s_addc_u32 s45, s45, 0
	s_add_i32 s48, s74, s76
	global_load_lds_dwordx4 v[154:155], off
	v_lshl_add_u64 v[154:155], s[44:45], 0, v[158:159]
	s_mov_b32 m0, s48
	s_nop 0
	global_load_lds_dwordx4 v[154:155], off
	v_lshl_add_u64 v[154:155], s[44:45], 0, v[162:163]
	s_add_i32 m0, s48, 0x2000
	s_nop 0
	global_load_lds_dwordx4 v[154:155], off
	v_lshl_add_u64 v[154:155], v[202:203], 0, s[56:57]
	s_mov_b32 m0, s88
	s_nop 0
	global_load_lds_dwordx4 v[154:155], off
	v_lshl_add_u64 v[154:155], v[234:235], 0, s[56:57]
	s_mov_b32 m0, s37
	s_nop 0
	global_load_lds_dwordx4 v[154:155], off
	s_waitcnt vmcnt(8)
	s_waitcnt lgkmcnt(0)
	s_setprio 1
	s_barrier
	v_mfma_f32_16x16x32_bf16 v[62:65], v[130:133], v[176:179], v[62:65]
	v_mfma_f32_16x16x32_bf16 v[58:61], v[138:141], v[176:179], v[58:61]
	v_mfma_f32_16x16x32_bf16 v[46:49], v[130:133], v[186:189], v[46:49]
	v_mfma_f32_16x16x32_bf16 v[42:45], v[138:141], v[186:189], v[42:45]
	v_mfma_f32_16x16x32_bf16 v[30:33], v[130:133], v[218:221], v[30:33]
	v_mfma_f32_16x16x32_bf16 v[26:29], v[138:141], v[218:221], v[26:29]
	v_mfma_f32_16x16x32_bf16 v[14:17], v[130:133], v[226:229], v[14:17]
	v_mfma_f32_16x16x32_bf16 v[10:13], v[138:141], v[226:229], v[10:13]
	v_mfma_f32_16x16x32_bf16 v[62:65], v[134:137], v[180:183], v[62:65]
	v_mfma_f32_16x16x32_bf16 v[58:61], v[142:145], v[180:183], v[58:61]
	v_mfma_f32_16x16x32_bf16 v[46:49], v[134:137], v[204:207], v[46:49]
	v_mfma_f32_16x16x32_bf16 v[42:45], v[142:145], v[204:207], v[42:45]
	v_mfma_f32_16x16x32_bf16 v[30:33], v[134:137], v[222:225], v[30:33]
	v_mfma_f32_16x16x32_bf16 v[26:29], v[142:145], v[222:225], v[26:29]
	v_mfma_f32_16x16x32_bf16 v[14:17], v[134:137], v[230:233], v[14:17]
	v_mfma_f32_16x16x32_bf16 v[10:13], v[142:145], v[230:233], v[10:13]
	s_setprio 0
	s_setprio 1
	v_mfma_f32_16x16x32_bf16 v[50:53], v[146:149], v[176:179], v[50:53]
	v_mfma_f32_16x16x32_bf16 v[54:57], v[168:171], v[176:179], v[54:57]
	v_mfma_f32_16x16x32_bf16 v[34:37], v[146:149], v[186:189], v[34:37]
	v_mfma_f32_16x16x32_bf16 v[38:41], v[168:171], v[186:189], v[38:41]
	v_mfma_f32_16x16x32_bf16 v[18:21], v[146:149], v[218:221], v[18:21]
	v_mfma_f32_16x16x32_bf16 v[22:25], v[168:171], v[218:221], v[22:25]
	v_mfma_f32_16x16x32_bf16 v[2:5], v[146:149], v[226:229], v[2:5]
	v_mfma_f32_16x16x32_bf16 v[6:9], v[168:171], v[226:229], v[6:9]
	v_mfma_f32_16x16x32_bf16 v[50:53], v[150:153], v[180:183], v[50:53]
	v_mfma_f32_16x16x32_bf16 v[54:57], v[172:175], v[180:183], v[54:57]
	v_mfma_f32_16x16x32_bf16 v[34:37], v[150:153], v[204:207], v[34:37]
	v_mfma_f32_16x16x32_bf16 v[38:41], v[172:175], v[204:207], v[38:41]
	v_mfma_f32_16x16x32_bf16 v[18:21], v[150:153], v[222:225], v[18:21]
	v_mfma_f32_16x16x32_bf16 v[22:25], v[172:175], v[222:225], v[22:25]
	v_mfma_f32_16x16x32_bf16 v[2:5], v[150:153], v[230:233], v[2:5]
	v_mfma_f32_16x16x32_bf16 v[6:9], v[172:175], v[230:233], v[6:9]
	s_barrier
	s_setprio 0
	s_add_i32 s51, s51, 2
	s_add_u32 s24, s24, 0x100
	s_addc_u32 s25, s25, 0
	s_add_u32 s27, s27, 0x100
	s_addc_u32 s47, s47, 0
	s_cmp_gt_u32 s51, 29
	s_cbranch_scc0 .LBB0_643
	s_and_b64 vcc, exec, s[68:69]
	s_cbranch_vccz .LBB0_646
	s_barrier

; #define PG8_STAGE(bufoff, gbase, voff) do { _Pragma("unroll") for (int _i = 0; _i < 2; ++_i) \
;         __builtin_amdgcn_global_load_lds((const unsigned*)((const char*)(gbase) + (voff)[_i]), (PG8_LAS unsigned*)(lds + (bufoff) + ldsw + _i * 8192), 16, 0, 0); } while (0)
; #define PG8_LDA(dst, b, h) do { _Pragma("unroll") for (int m = 0; m < 4; ++m) _Pragma("unroll") for (int k = 0; k < 2; ++k) dst[m][k] = *(const PG8_LAS bf16x8*)(lds + PG8_SA(b, h) + aoff + m * 2048 + k * 1024); } while (0)
; #define PG8_LDB(dst, b, h) do { _Pragma("unroll") for (int n = 0; n < 2; ++n) _Pragma("unroll") for (int k = 0; k < 2; ++k) dst[n][k] = *(const PG8_LAS bf16x8*)(lds + PG8_SB(b, h) + boff + n * 2048 + k * 1024); } while (0)
; #define PG8_MMA(ai, bj, At, Bt) do { __builtin_amdgcn_s_setprio(1); _Pragma("unroll") for (int m = 0; m < 4; ++m) _Pragma("unroll") for (int n = 0; n < 2; ++n) _Pragma("unroll") for (int k = 0; k < 2; ++k) \
;         acc[ai][bj][m][n] = __builtin_amdgcn_mfma_f32_16x16x32_bf16(Bt[n][k], At[m][k], acc[ai][bj][m][n], 0, 0, 0); __builtin_amdgcn_s_setprio(0); } while (0)
; #define PG8_WAIT_V(n) asm volatile("s_waitcnt vmcnt(" #n ")" ::: "memory")
; #define PG8_WAIT_L(n) asm volatile("s_waitcnt lgkmcnt(" #n ")" ::: "memory")
; template <class Epi, class Sched, bool ALIGN_EPI = false, bool SP2 = false>
; __device__ __forceinline__ void gemm_phase(PG8_LAS unsigned char* lds, const Gemm g, const Sched& S, const Epi& E) {
;     ...
;             const bool last = (t == nt - 2);
;             const char* a1 = cA + (size_t)(t + 1) * kstep;
;             const char* a2 = last ? nA : cA + (size_t)(t + 2) * kstep; const char* b2 = last ? nB : cB + (size_t)(t + 2) * kstep;
;             const char* a3 = a2 + kstep; const char* b3 = b2 + kstep;
;             if (last && has_next) S.a_ready(nxt);
;             if constexpr (SP2) {
;             PG8_LDB(B0, 0, 0); PG8_LDB(B1, 0, 1); PG8_SCHED; PG8_LDA(At, 0, 0); PG8_STAGE(PG8_SA(1, 1), a1 + hstep, voffA);
;             PG8_WAIT_V(8); PG8_WAIT_L(0); PG8_BAR; PG8_MMA(0, 0, At, B0); PG8_MMA(0, 1, At, B1); PG8_BAR; PG8_SCHED;
;             PG8_LDA(At, 0, 1); PG8_STAGE(PG8_SB(0, 0), b2, voffB); PG8_STAGE(PG8_SB(0, 1), b2 + hstep, voffB); PG8_STAGE(PG8_SA(0, 0), a2, voffA);
;             PG8_WAIT_V(8); PG8_WAIT_L(0); PG8_BAR; PG8_MMA(1, 0, At, B0); PG8_MMA(1, 1, At, B1); PG8_BAR; PG8_SCHED;
.LBB0_1000:
	s_add_u32 s24, s22, 0x100
	s_addc_u32 s25, s23, 0
	s_add_i32 s59, 0, 0x10000
	s_cmpk_eq_i32 s58, 0x54
	s_cselect_b32 s45, s19, s25
	s_cselect_b32 s44, s18, s24
	s_cselect_b32 s41, s21, s55
	s_cselect_b32 s40, s20, s54
	s_add_i32 s62, 0, 0x14000
	v_add_u32_e32 v152, s59, v163
	v_add_u32_e32 v160, s62, v163
	ds_read_b128 v[130:133], v152
	ds_read_b128 v[134:137], v152 offset:1024
	ds_read_b128 v[138:141], v152 offset:2048
	ds_read_b128 v[152:155], v152 offset:3072
	ds_read_b128 v[156:159], v160
	ds_read_b128 v[166:169], v160 offset:1024
	ds_read_b128 v[170:173], v160 offset:2048
	ds_read_b128 v[174:177], v160 offset:3072
	v_lshl_add_u64 v[160:161], s[22:23], 0, v[148:149]
	s_add_i32 m0, s2, 0xc000
	ds_read_b128 v[178:181], v165
	ds_read_b128 v[182:185], v165 offset:1024
	ds_read_b128 v[186:189], v165 offset:2048
	ds_read_b128 v[190:193], v165 offset:3072
	ds_read_b128 v[204:207], v165 offset:4096
	ds_read_b128 v[218:221], v165 offset:5120
	ds_read_b128 v[222:225], v165 offset:6144
	ds_read_b128 v[226:229], v165 offset:7168
	global_load_lds_dwordx4 v[160:161], off
	v_lshl_add_u64 v[160:161], s[22:23], 0, v[150:151]
	s_add_i32 m0, s2, 0xe000
	s_nop 0
	global_load_lds_dwordx4 v[160:161], off
	s_waitcnt vmcnt(8)
	s_waitcnt lgkmcnt(0)
	s_setprio 1
	s_barrier
	v_mfma_f32_16x16x32_bf16 v[126:129], v[130:133], v[178:181], v[126:129]
	v_mfma_f32_16x16x32_bf16 v[122:125], v[138:141], v[178:181], v[122:125]
	v_mfma_f32_16x16x32_bf16 v[110:113], v[130:133], v[186:189], v[110:113]
	v_mfma_f32_16x16x32_bf16 v[106:109], v[138:141], v[186:189], v[106:109]
	v_mfma_f32_16x16x32_bf16 v[94:97], v[130:133], v[204:207], v[94:97]
	v_mfma_f32_16x16x32_bf16 v[90:93], v[138:141], v[204:207], v[90:93]
	v_mfma_f32_16x16x32_bf16 v[78:81], v[130:133], v[222:225], v[78:81]
	v_mfma_f32_16x16x32_bf16 v[74:77], v[138:141], v[222:225], v[74:77]
	v_mfma_f32_16x16x32_bf16 v[126:129], v[134:137], v[182:185], v[126:129]
	v_mfma_f32_16x16x32_bf16 v[122:125], v[152:155], v[182:185], v[122:125]
	v_mfma_f32_16x16x32_bf16 v[110:113], v[134:137], v[190:193], v[110:113]
	v_mfma_f32_16x16x32_bf16 v[106:109], v[152:155], v[190:193], v[106:109]
	v_mfma_f32_16x16x32_bf16 v[94:97], v[134:137], v[218:221], v[94:97]
	v_mfma_f32_16x16x32_bf16 v[90:93], v[152:155], v[218:221], v[90:93]
	v_mfma_f32_16x16x32_bf16 v[78:81], v[134:137], v[226:229], v[78:81]
	v_mfma_f32_16x16x32_bf16 v[74:77], v[152:155], v[226:229], v[74:77]
	s_setprio 0
	s_setprio 1
	v_mfma_f32_16x16x32_bf16 v[118:121], v[156:159], v[178:181], v[118:121]
	v_mfma_f32_16x16x32_bf16 v[114:117], v[170:173], v[178:181], v[114:117]
	v_mfma_f32_16x16x32_bf16 v[102:105], v[156:159], v[186:189], v[102:105]
	v_mfma_f32_16x16x32_bf16 v[98:101], v[170:173], v[186:189], v[98:101]
	v_mfma_f32_16x16x32_bf16 v[86:89], v[156:159], v[204:207], v[86:89]
	v_mfma_f32_16x16x32_bf16 v[82:85], v[170:173], v[204:207], v[82:85]
	v_mfma_f32_16x16x32_bf16 v[70:73], v[156:159], v[222:225], v[70:73]
	v_mfma_f32_16x16x32_bf16 v[66:69], v[170:173], v[222:225], v[66:69]
	v_mfma_f32_16x16x32_bf16 v[118:121], v[166:169], v[182:185], v[118:121]
	v_mfma_f32_16x16x32_bf16 v[114:117], v[174:177], v[182:185], v[114:117]
	v_mfma_f32_16x16x32_bf16 v[102:105], v[166:169], v[190:193], v[102:105]
	v_mfma_f32_16x16x32_bf16 v[98:101], v[174:177], v[190:193], v[98:101]
	v_mfma_f32_16x16x32_bf16 v[86:89], v[166:169], v[218:221], v[86:89]
	v_mfma_f32_16x16x32_bf16 v[82:85], v[174:177], v[218:221], v[82:85]
	v_mfma_f32_16x16x32_bf16 v[70:73], v[166:169], v[226:229], v[70:73]
	v_mfma_f32_16x16x32_bf16 v[66:69], v[174:177], v[226:229], v[66:69]
	s_barrier
	s_setprio 0
	s_add_i32 s22, s59, s1
	v_lshl_add_u64 v[160:161], s[40:41], 0, v[0:1]
	s_mov_b32 m0, s22
	ds_read_b128 v[178:181], v165 offset:16384
	ds_read_b128 v[182:185], v165 offset:17408
	ds_read_b128 v[186:189], v165 offset:18432
	ds_read_b128 v[190:193], v165 offset:19456
	ds_read_b128 v[204:207], v165 offset:20480
	ds_read_b128 v[218:221], v165 offset:21504
	ds_read_b128 v[222:225], v165 offset:22528
	ds_read_b128 v[226:229], v165 offset:23552
	global_load_lds_dwordx4 v[160:161], off
	s_add_i32 m0, s22, 0x2000
	s_add_u32 s22, s40, 0x160000
	v_lshl_add_u64 v[200:201], s[40:41], 0, v[146:147]
	s_addc_u32 s23, s41, 0
	s_add_i32 s59, s62, s1
	global_load_lds_dwordx4 v[200:201], off
	v_lshl_add_u64 v[202:203], s[22:23], 0, v[0:1]
	s_mov_b32 m0, s59
	v_lshl_add_u64 v[230:231], s[44:45], 0, v[144:145]
	global_load_lds_dwordx4 v[202:203], off
	v_lshl_add_u64 v[202:203], s[22:23], 0, v[146:147]
	s_add_i32 m0, s59, 0x2000
	s_nop 0
	global_load_lds_dwordx4 v[202:203], off
	v_lshl_add_u64 v[202:203], s[44:45], 0, v[142:143]
	s_mov_b32 m0, s2
	s_nop 0
	global_load_lds_dwordx4 v[202:203], off
	s_mov_b32 m0, s3
	s_nop 0
	global_load_lds_dwordx4 v[230:231], off
	s_waitcnt vmcnt(8)
	s_waitcnt lgkmcnt(0)
	s_setprio 1
	s_barrier
; #define PG8_STAGE(bufoff, gbase, voff) do { _Pragma("unroll") for (int _i = 0; _i < 2; ++_i) \
;         __builtin_amdgcn_global_load_lds((const unsigned*)((const char*)(gbase) + (voff)[_i]), (PG8_LAS unsigned*)(lds + (bufoff) + ldsw + _i * 8192), 16, 0, 0); } while (0)
; #define PG8_LDA(dst, b, h) do { _Pragma("unroll") for (int m = 0; m < 4; ++m) _Pragma("unroll") for (int k = 0; k < 2; ++k) dst[m][k] = *(const PG8_LAS bf16x8*)(lds + PG8_SA(b, h) + aoff + m * 2048 + k * 1024); } while (0)
; #define PG8_LDB(dst, b, h) do { _Pragma("unroll") for (int n = 0; n < 2; ++n) _Pragma("unroll") for (int k = 0; k < 2; ++k) dst[n][k] = *(const PG8_LAS bf16x8*)(lds + PG8_SB(b, h) + boff + n * 2048 + k * 1024); } while (0)
; #define PG8_MMA(ai, bj, At, Bt) do { __builtin_amdgcn_s_setprio(1); _Pragma("unroll") for (int m = 0; m < 4; ++m) _Pragma("unroll") for (int n = 0; n < 2; ++n) _Pragma("unroll") for (int k = 0; k < 2; ++k) \
;         acc[ai][bj][m][n] = __builtin_amdgcn_mfma_f32_16x16x32_bf16(Bt[n][k], At[m][k], acc[ai][bj][m][n], 0, 0, 0); __builtin_amdgcn_s_setprio(0); } while (0)
; #define PG8_WAIT_V(n) asm volatile("s_waitcnt vmcnt(" #n ")" ::: "memory")
; #define PG8_WAIT_L(n) asm volatile("s_waitcnt lgkmcnt(" #n ")" ::: "memory")
; #define PG8_BAR __builtin_amdgcn_s_barrier()
; #define PG8_SCHED __builtin_amdgcn_sched_barrier(0)
; template <class Epi, class Sched, bool ALIGN_EPI = false, bool SP2 = false>
; __device__ __forceinline__ void gemm_phase(PG8_LAS unsigned char* lds, const Gemm g, const Sched& S, const Epi& E) {
;     ...
;             PG8_WAIT_V(8); PG8_WAIT_L(0); PG8_BAR; PG8_MMA(1, 0, At, B0); PG8_MMA(1, 1, At, B1); PG8_BAR; PG8_SCHED;
;             PG8_LDB(B0, 1, 0); PG8_LDB(B1, 1, 1); PG8_SCHED; PG8_LDA(At, 1, 0); PG8_STAGE(PG8_SA(0, 1), a2 + hstep, voffA);
;             PG8_WAIT_V(8); PG8_WAIT_L(0); PG8_BAR; PG8_MMA(0, 0, At, B0); PG8_MMA(0, 1, At, B1); PG8_BAR; PG8_SCHED;
	v_mfma_f32_16x16x32_bf16 v[62:65], v[130:133], v[178:181], v[62:65]
	v_mfma_f32_16x16x32_bf16 v[58:61], v[138:141], v[178:181], v[58:61]
	v_mfma_f32_16x16x32_bf16 v[46:49], v[130:133], v[186:189], v[46:49]
	v_mfma_f32_16x16x32_bf16 v[42:45], v[138:141], v[186:189], v[42:45]
	v_mfma_f32_16x16x32_bf16 v[30:33], v[130:133], v[204:207], v[30:33]
	v_mfma_f32_16x16x32_bf16 v[26:29], v[138:141], v[204:207], v[26:29]
	v_mfma_f32_16x16x32_bf16 v[14:17], v[130:133], v[222:225], v[14:17]
	v_mfma_f32_16x16x32_bf16 v[10:13], v[138:141], v[222:225], v[10:13]
	v_mfma_f32_16x16x32_bf16 v[62:65], v[134:137], v[182:185], v[62:65]
	v_mfma_f32_16x16x32_bf16 v[58:61], v[152:155], v[182:185], v[58:61]
	v_mfma_f32_16x16x32_bf16 v[46:49], v[134:137], v[190:193], v[46:49]
	v_mfma_f32_16x16x32_bf16 v[42:45], v[152:155], v[190:193], v[42:45]
	v_mfma_f32_16x16x32_bf16 v[30:33], v[134:137], v[218:221], v[30:33]
	v_mfma_f32_16x16x32_bf16 v[26:29], v[152:155], v[218:221], v[26:29]
	v_mfma_f32_16x16x32_bf16 v[14:17], v[134:137], v[226:229], v[14:17]
	v_mfma_f32_16x16x32_bf16 v[10:13], v[152:155], v[226:229], v[10:13]
	s_setprio 0
	s_setprio 1
	v_mfma_f32_16x16x32_bf16 v[54:57], v[156:159], v[178:181], v[54:57]
	v_mfma_f32_16x16x32_bf16 v[50:53], v[170:173], v[178:181], v[50:53]
	v_mfma_f32_16x16x32_bf16 v[38:41], v[156:159], v[186:189], v[38:41]
	v_mfma_f32_16x16x32_bf16 v[34:37], v[170:173], v[186:189], v[34:37]
	v_mfma_f32_16x16x32_bf16 v[22:25], v[156:159], v[204:207], v[22:25]
	v_mfma_f32_16x16x32_bf16 v[18:21], v[170:173], v[204:207], v[18:21]
	v_mfma_f32_16x16x32_bf16 v[6:9], v[156:159], v[222:225], v[6:9]
	v_mfma_f32_16x16x32_bf16 v[2:5], v[170:173], v[222:225], v[2:5]
	v_mfma_f32_16x16x32_bf16 v[54:57], v[166:169], v[182:185], v[54:57]
	v_mfma_f32_16x16x32_bf16 v[50:53], v[174:177], v[182:185], v[50:53]
	v_mfma_f32_16x16x32_bf16 v[38:41], v[166:169], v[190:193], v[38:41]
	v_mfma_f32_16x16x32_bf16 v[34:37], v[174:177], v[190:193], v[34:37]
	v_mfma_f32_16x16x32_bf16 v[22:25], v[166:169], v[218:221], v[22:25]
	v_mfma_f32_16x16x32_bf16 v[18:21], v[174:177], v[218:221], v[18:21]
	v_mfma_f32_16x16x32_bf16 v[6:9], v[166:169], v[226:229], v[6:9]
	v_mfma_f32_16x16x32_bf16 v[2:5], v[174:177], v[226:229], v[2:5]
	s_barrier
	s_setprio 0
	s_add_i32 s59, 0, 0x18000
	s_add_i32 s62, 0, 0x1c000
	v_add_u32_e32 v152, s59, v163
	v_add_u32_e32 v174, s62, v163
	ds_read_b128 v[130:133], v152
	ds_read_b128 v[134:137], v152 offset:1024
	ds_read_b128 v[138:141], v152 offset:2048
	ds_read_b128 v[152:155], v152 offset:3072
	ds_read_b128 v[156:159], v174
	ds_read_b128 v[166:169], v174 offset:1024
	ds_read_b128 v[170:173], v174 offset:2048
	ds_read_b128 v[174:177], v174 offset:3072
	s_add_u32 s22, s44, 0x160000
	s_addc_u32 s23, s45, 0
	s_mov_b32 m0, s10
	v_lshl_add_u64 v[232:233], s[22:23], 0, v[142:143]
	ds_read_b128 v[178:181], v165 offset:32768
	ds_read_b128 v[182:185], v165 offset:33792
	ds_read_b128 v[186:189], v165 offset:34816
	ds_read_b128 v[190:193], v165 offset:35840
	ds_read_b128 v[204:207], v165 offset:36864
	ds_read_b128 v[218:221], v165 offset:37888
	ds_read_b128 v[222:225], v165 offset:38912
	ds_read_b128 v[226:229], v165 offset:39936
	global_load_lds_dwordx4 v[232:233], off
	v_lshl_add_u64 v[232:233], s[22:23], 0, v[144:145]
	s_mov_b32 m0, s11
	s_nop 0
	global_load_lds_dwordx4 v[232:233], off
	s_waitcnt vmcnt(8)
	s_waitcnt lgkmcnt(0)
	s_setprio 1
	s_barrier
	v_mfma_f32_16x16x32_bf16 v[126:129], v[130:133], v[178:181], v[126:129]
	v_mfma_f32_16x16x32_bf16 v[122:125], v[138:141], v[178:181], v[122:125]
	v_mfma_f32_16x16x32_bf16 v[110:113], v[130:133], v[186:189], v[110:113]
	v_mfma_f32_16x16x32_bf16 v[106:109], v[138:141], v[186:189], v[106:109]
	v_mfma_f32_16x16x32_bf16 v[94:97], v[130:133], v[204:207], v[94:97]
	v_mfma_f32_16x16x32_bf16 v[90:93], v[138:141], v[204:207], v[90:93]
	v_mfma_f32_16x16x32_bf16 v[78:81], v[130:133], v[222:225], v[78:81]
	v_mfma_f32_16x16x32_bf16 v[74:77], v[138:141], v[222:225], v[74:77]
	v_mfma_f32_16x16x32_bf16 v[126:129], v[134:137], v[182:185], v[126:129]
	v_mfma_f32_16x16x32_bf16 v[122:125], v[152:155], v[182:185], v[122:125]
	v_mfma_f32_16x16x32_bf16 v[110:113], v[134:137], v[190:193], v[110:113]
	v_mfma_f32_16x16x32_bf16 v[106:109], v[152:155], v[190:193], v[106:109]
	v_mfma_f32_16x16x32_bf16 v[94:97], v[134:137], v[218:221], v[94:97]
	v_mfma_f32_16x16x32_bf16 v[90:93], v[152:155], v[218:221], v[90:93]
	v_mfma_f32_16x16x32_bf16 v[78:81], v[134:137], v[226:229], v[78:81]
	v_mfma_f32_16x16x32_bf16 v[74:77], v[152:155], v[226:229], v[74:77]
	s_setprio 0
	s_setprio 1
	v_mfma_f32_16x16x32_bf16 v[118:121], v[156:159], v[178:181], v[118:121]
	v_mfma_f32_16x16x32_bf16 v[114:117], v[170:173], v[178:181], v[114:117]
	v_mfma_f32_16x16x32_bf16 v[102:105], v[156:159], v[186:189], v[102:105]
	v_mfma_f32_16x16x32_bf16 v[98:101], v[170:173], v[186:189], v[98:101]
	v_mfma_f32_16x16x32_bf16 v[86:89], v[156:159], v[204:207], v[86:89]
	v_mfma_f32_16x16x32_bf16 v[82:85], v[170:173], v[204:207], v[82:85]
	v_mfma_f32_16x16x32_bf16 v[70:73], v[156:159], v[222:225], v[70:73]
	v_mfma_f32_16x16x32_bf16 v[66:69], v[170:173], v[222:225], v[66:69]
	v_mfma_f32_16x16x32_bf16 v[118:121], v[166:169], v[182:185], v[118:121]
	v_mfma_f32_16x16x32_bf16 v[114:117], v[174:177], v[182:185], v[114:117]
	v_mfma_f32_16x16x32_bf16 v[102:105], v[166:169], v[190:193], v[102:105]
	v_mfma_f32_16x16x32_bf16 v[98:101], v[174:177], v[190:193], v[98:101]
	v_mfma_f32_16x16x32_bf16 v[86:89], v[166:169], v[218:221], v[86:89]
	v_mfma_f32_16x16x32_bf16 v[82:85], v[174:177], v[218:221], v[82:85]
	v_mfma_f32_16x16x32_bf16 v[70:73], v[166:169], v[226:229], v[70:73]
	v_mfma_f32_16x16x32_bf16 v[66:69], v[174:177], v[226:229], v[66:69]
	s_barrier
; #define PG8_STAGE(bufoff, gbase, voff) do { _Pragma("unroll") for (int _i = 0; _i < 2; ++_i) \
;         __builtin_amdgcn_global_load_lds((const unsigned*)((const char*)(gbase) + (voff)[_i]), (PG8_LAS unsigned*)(lds + (bufoff) + ldsw + _i * 8192), 16, 0, 0); } while (0)
; #define PG8_LDA(dst, b, h) do { _Pragma("unroll") for (int m = 0; m < 4; ++m) _Pragma("unroll") for (int k = 0; k < 2; ++k) dst[m][k] = *(const PG8_LAS bf16x8*)(lds + PG8_SA(b, h) + aoff + m * 2048 + k * 1024); } while (0)
; #define PG8_MMA(ai, bj, At, Bt) do { __builtin_amdgcn_s_setprio(1); _Pragma("unroll") for (int m = 0; m < 4; ++m) _Pragma("unroll") for (int n = 0; n < 2; ++n) _Pragma("unroll") for (int k = 0; k < 2; ++k) \
;         acc[ai][bj][m][n] = __builtin_amdgcn_mfma_f32_16x16x32_bf16(Bt[n][k], At[m][k], acc[ai][bj][m][n], 0, 0, 0); __builtin_amdgcn_s_setprio(0); } while (0)
; #define PG8_WAIT_V(n) asm volatile("s_waitcnt vmcnt(" #n ")" ::: "memory")
; #define PG8_WAIT_L(n) asm volatile("s_waitcnt lgkmcnt(" #n ")" ::: "memory")
; #define PG8_BAR __builtin_amdgcn_s_barrier()
; #define PG8_SCHED __builtin_amdgcn_sched_barrier(0)
; template <class Epi, class Sched, bool ALIGN_EPI = false, bool SP2 = false>
; __device__ __forceinline__ void gemm_phase(PG8_LAS unsigned char* lds, const Gemm g, const Sched& S, const Epi& E) {
;     ...
;         for (int t = 0; t < nt; t += 2) {
;             const bool last = (t == nt - 2);
;             const char* a1 = cA + (size_t)(t + 1) * kstep;
;             const char* a2 = last ? nA : cA + (size_t)(t + 2) * kstep; const char* b2 = last ? nB : cB + (size_t)(t + 2) * kstep;
;     ...
;             PG8_LDA(At, 1, 1); PG8_STAGE(PG8_SB(1, 0), b3, voffB); PG8_STAGE(PG8_SB(1, 1), b3 + hstep, voffB); PG8_STAGE(PG8_SA(1, 0), a3, voffA);
;             PG8_WAIT_V(8); PG8_WAIT_L(0); PG8_BAR; PG8_MMA(1, 0, At, B0); PG8_MMA(1, 1, At, B1); PG8_BAR; PG8_SCHED;
	s_setprio 0
	s_add_i32 s22, s59, s1
	v_lshl_add_u64 v[160:161], v[160:161], 0, s[56:57]
	s_mov_b32 m0, s22
	ds_read_b128 v[178:181], v165 offset:49152
	ds_read_b128 v[182:185], v165 offset:50176
	ds_read_b128 v[186:189], v165 offset:51200
	ds_read_b128 v[190:193], v165 offset:52224
	ds_read_b128 v[204:207], v165 offset:53248
	ds_read_b128 v[218:221], v165 offset:54272
	ds_read_b128 v[222:225], v165 offset:55296
	ds_read_b128 v[226:229], v165 offset:56320
	global_load_lds_dwordx4 v[160:161], off
	s_add_i32 m0, s22, 0x2000
	s_add_u32 s22, s40, 0x160080
	v_lshl_add_u64 v[160:161], v[200:201], 0, s[56:57]
	s_addc_u32 s23, s41, 0
	s_add_i32 s40, s62, s1
	global_load_lds_dwordx4 v[160:161], off
	v_lshl_add_u64 v[160:161], s[22:23], 0, v[0:1]
	s_mov_b32 m0, s40
	s_nop 0
	global_load_lds_dwordx4 v[160:161], off
	v_lshl_add_u64 v[160:161], s[22:23], 0, v[146:147]
	s_add_i32 m0, s40, 0x2000
	s_nop 0
	global_load_lds_dwordx4 v[160:161], off
	v_lshl_add_u64 v[160:161], v[202:203], 0, s[56:57]
	s_mov_b32 m0, s37
	s_nop 0
	global_load_lds_dwordx4 v[160:161], off
	v_lshl_add_u64 v[160:161], v[230:231], 0, s[56:57]
	s_mov_b32 m0, s46
	s_nop 0
	global_load_lds_dwordx4 v[160:161], off
	s_waitcnt vmcnt(8)
	s_waitcnt lgkmcnt(0)
	s_setprio 1
	s_barrier
	v_mfma_f32_16x16x32_bf16 v[62:65], v[130:133], v[178:181], v[62:65]
	v_mfma_f32_16x16x32_bf16 v[58:61], v[138:141], v[178:181], v[58:61]
	v_mfma_f32_16x16x32_bf16 v[46:49], v[130:133], v[186:189], v[46:49]
	v_mfma_f32_16x16x32_bf16 v[42:45], v[138:141], v[186:189], v[42:45]
	v_mfma_f32_16x16x32_bf16 v[30:33], v[130:133], v[204:207], v[30:33]
	v_mfma_f32_16x16x32_bf16 v[26:29], v[138:141], v[204:207], v[26:29]
	v_mfma_f32_16x16x32_bf16 v[14:17], v[130:133], v[222:225], v[14:17]
	v_mfma_f32_16x16x32_bf16 v[10:13], v[138:141], v[222:225], v[10:13]
	v_mfma_f32_16x16x32_bf16 v[62:65], v[134:137], v[182:185], v[62:65]
	v_mfma_f32_16x16x32_bf16 v[58:61], v[152:155], v[182:185], v[58:61]
	v_mfma_f32_16x16x32_bf16 v[46:49], v[134:137], v[190:193], v[46:49]
	v_mfma_f32_16x16x32_bf16 v[42:45], v[152:155], v[190:193], v[42:45]
	v_mfma_f32_16x16x32_bf16 v[30:33], v[134:137], v[218:221], v[30:33]
	v_mfma_f32_16x16x32_bf16 v[26:29], v[152:155], v[218:221], v[26:29]
	v_mfma_f32_16x16x32_bf16 v[14:17], v[134:137], v[226:229], v[14:17]
	v_mfma_f32_16x16x32_bf16 v[10:13], v[152:155], v[226:229], v[10:13]
	s_setprio 0
	s_setprio 1
	v_mfma_f32_16x16x32_bf16 v[54:57], v[156:159], v[178:181], v[54:57]
	v_mfma_f32_16x16x32_bf16 v[50:53], v[170:173], v[178:181], v[50:53]
	v_mfma_f32_16x16x32_bf16 v[38:41], v[156:159], v[186:189], v[38:41]
	v_mfma_f32_16x16x32_bf16 v[34:37], v[170:173], v[186:189], v[34:37]
	v_mfma_f32_16x16x32_bf16 v[22:25], v[156:159], v[204:207], v[22:25]
	v_mfma_f32_16x16x32_bf16 v[18:21], v[170:173], v[204:207], v[18:21]
	v_mfma_f32_16x16x32_bf16 v[6:9], v[156:159], v[222:225], v[6:9]
	v_mfma_f32_16x16x32_bf16 v[2:5], v[170:173], v[222:225], v[2:5]
	v_mfma_f32_16x16x32_bf16 v[54:57], v[166:169], v[182:185], v[54:57]
	v_mfma_f32_16x16x32_bf16 v[50:53], v[174:177], v[182:185], v[50:53]
	v_mfma_f32_16x16x32_bf16 v[38:41], v[166:169], v[190:193], v[38:41]
	v_mfma_f32_16x16x32_bf16 v[34:37], v[174:177], v[190:193], v[34:37]
	v_mfma_f32_16x16x32_bf16 v[22:25], v[166:169], v[218:221], v[22:25]
	v_mfma_f32_16x16x32_bf16 v[18:21], v[174:177], v[218:221], v[18:21]
	v_mfma_f32_16x16x32_bf16 v[6:9], v[166:169], v[226:229], v[6:9]
	v_mfma_f32_16x16x32_bf16 v[2:5], v[174:177], v[226:229], v[2:5]
	s_barrier
	s_setprio 0
	s_add_i32 s58, s58, 2
	s_add_u32 s54, s54, 0x100
	s_addc_u32 s55, s55, 0
	s_cmpk_gt_u32 s58, 0x55
	s_mov_b64 s[22:23], s[24:25]
	s_cbranch_scc0 .LBB0_1000
	s_and_b64 vcc, exec, s[16:17]
	s_cbranch_vccz .LBB0_1003
	s_barrier

; #define PG8_STAGE(bufoff, gbase, voff) do { _Pragma("unroll") for (int _i = 0; _i < 2; ++_i) \
;         __builtin_amdgcn_global_load_lds((const unsigned*)((const char*)(gbase) + (voff)[_i]), (PG8_LAS unsigned*)(lds + (bufoff) + ldsw + _i * 8192), 16, 0, 0); } while (0)
; #define PG8_LDA(dst, b, h) do { _Pragma("unroll") for (int m = 0; m < 4; ++m) _Pragma("unroll") for (int k = 0; k < 2; ++k) dst[m][k] = *(const PG8_LAS bf16x8*)(lds + PG8_SA(b, h) + aoff + m * 2048 + k * 1024); } while (0)
; #define PG8_LDB(dst, b, h) do { _Pragma("unroll") for (int n = 0; n < 2; ++n) _Pragma("unroll") for (int k = 0; k < 2; ++k) dst[n][k] = *(const PG8_LAS bf16x8*)(lds + PG8_SB(b, h) + boff + n * 2048 + k * 1024); } while (0)
; #define PG8_MMA(ai, bj, At, Bt) do { __builtin_amdgcn_s_setprio(1); _Pragma("unroll") for (int m = 0; m < 4; ++m) _Pragma("unroll") for (int n = 0; n < 2; ++n) _Pragma("unroll") for (int k = 0; k < 2; ++k) \
;         acc[ai][bj][m][n] = __builtin_amdgcn_mfma_f32_16x16x32_bf16(Bt[n][k], At[m][k], acc[ai][bj][m][n], 0, 0, 0); __builtin_amdgcn_s_setprio(0); } while (0)
; #define PG8_WAIT_V(n) asm volatile("s_waitcnt vmcnt(" #n ")" ::: "memory")
; #define PG8_WAIT_L(n) asm volatile("s_waitcnt lgkmcnt(" #n ")" ::: "memory")
; template <class Epi, class Sched, bool ALIGN_EPI = false, bool SP2 = false>
; __device__ __forceinline__ void gemm_phase(PG8_LAS unsigned char* lds, const Gemm g, const Sched& S, const Epi& E) {
;     ...
;             const bool last = (t == nt - 2);
;             const char* a1 = cA + (size_t)(t + 1) * kstep;
;             const char* a2 = last ? nA : cA + (size_t)(t + 2) * kstep; const char* b2 = last ? nB : cB + (size_t)(t + 2) * kstep;
;             const char* a3 = a2 + kstep; const char* b3 = b2 + kstep;
;             if (last && has_next) S.a_ready(nxt);
;             if constexpr (SP2) {
;             PG8_LDB(B0, 0, 0); PG8_LDB(B1, 0, 1); PG8_SCHED; PG8_LDA(At, 0, 0); PG8_STAGE(PG8_SA(1, 1), a1 + hstep, voffA);
;             PG8_WAIT_V(8); PG8_WAIT_L(0); PG8_BAR; PG8_MMA(0, 0, At, B0); PG8_MMA(0, 1, At, B1); PG8_BAR; PG8_SCHED;
;             PG8_LDA(At, 0, 1); PG8_STAGE(PG8_SB(0, 0), b2, voffB); PG8_STAGE(PG8_SB(0, 1), b2 + hstep, voffB); PG8_STAGE(PG8_SA(0, 0), a2, voffA);
;             PG8_WAIT_V(8); PG8_WAIT_L(0); PG8_BAR; PG8_MMA(1, 0, At, B0); PG8_MMA(1, 1, At, B1); PG8_BAR; PG8_SCHED;
.LBB0_1027:
	s_add_u32 s20, s18, 0x100
	s_addc_u32 s21, s19, 0
	s_cmp_lg_u32 s38, 18
	s_cselect_b32 s22, s20, 0
	s_cselect_b32 s23, s21, 0
	s_add_u32 s24, s16, s22
	s_addc_u32 s25, s17, s23
	s_add_i32 s39, 0, 0x10000
	s_add_u32 s22, s14, s22
	s_addc_u32 s23, s15, s23
	s_add_i32 s40, 0, 0x14000
	v_add_u32_e32 v156, s39, v142
	v_add_u32_e32 v172, s40, v142
	ds_read_b128 v[144:147], v156
	ds_read_b128 v[148:151], v156 offset:1024
	ds_read_b128 v[152:155], v156 offset:2048
	ds_read_b128 v[156:159], v156 offset:3072
	ds_read_b128 v[160:163], v172
	ds_read_b128 v[164:167], v172 offset:1024
	ds_read_b128 v[168:171], v172 offset:2048
	ds_read_b128 v[172:175], v172 offset:3072
	v_lshl_add_u64 v[192:193], v[138:139], 0, s[18:19]
	s_add_i32 m0, s3, 0xc000
	ds_read_b128 v[176:179], v143
	ds_read_b128 v[180:183], v143 offset:1024
	ds_read_b128 v[184:187], v143 offset:2048
	ds_read_b128 v[188:191], v143 offset:3072
	ds_read_b128 v[204:207], v143 offset:4096
	ds_read_b128 v[218:221], v143 offset:5120
	ds_read_b128 v[222:225], v143 offset:6144
	ds_read_b128 v[226:229], v143 offset:7168
	global_load_lds_dwordx4 v[192:193], off
	v_lshl_add_u64 v[192:193], v[140:141], 0, s[18:19]
	s_add_i32 m0, s3, 0xe000
	s_nop 0
	global_load_lds_dwordx4 v[192:193], off
	s_waitcnt vmcnt(8)
	s_waitcnt lgkmcnt(0)
	s_setprio 1
	s_barrier
	v_mfma_f32_16x16x32_bf16 v[58:61], v[144:147], v[176:179], v[58:61]
	v_mfma_f32_16x16x32_bf16 v[62:65], v[152:155], v[176:179], v[62:65]
	v_mfma_f32_16x16x32_bf16 v[42:45], v[144:147], v[184:187], v[42:45]
	v_mfma_f32_16x16x32_bf16 v[46:49], v[152:155], v[184:187], v[46:49]
	v_mfma_f32_16x16x32_bf16 v[26:29], v[144:147], v[204:207], v[26:29]
	v_mfma_f32_16x16x32_bf16 v[30:33], v[152:155], v[204:207], v[30:33]
	v_mfma_f32_16x16x32_bf16 v[10:13], v[144:147], v[222:225], v[10:13]
	v_mfma_f32_16x16x32_bf16 v[14:17], v[152:155], v[222:225], v[14:17]
	v_mfma_f32_16x16x32_bf16 v[58:61], v[148:151], v[180:183], v[58:61]
	v_mfma_f32_16x16x32_bf16 v[62:65], v[156:159], v[180:183], v[62:65]
	v_mfma_f32_16x16x32_bf16 v[42:45], v[148:151], v[188:191], v[42:45]
	v_mfma_f32_16x16x32_bf16 v[46:49], v[156:159], v[188:191], v[46:49]
	v_mfma_f32_16x16x32_bf16 v[26:29], v[148:151], v[218:221], v[26:29]
	v_mfma_f32_16x16x32_bf16 v[30:33], v[156:159], v[218:221], v[30:33]
	v_mfma_f32_16x16x32_bf16 v[10:13], v[148:151], v[226:229], v[10:13]
	v_mfma_f32_16x16x32_bf16 v[14:17], v[156:159], v[226:229], v[14:17]
	s_setprio 0
	s_setprio 1
	v_mfma_f32_16x16x32_bf16 v[50:53], v[160:163], v[176:179], v[50:53]
	v_mfma_f32_16x16x32_bf16 v[54:57], v[168:171], v[176:179], v[54:57]
	v_mfma_f32_16x16x32_bf16 v[34:37], v[160:163], v[184:187], v[34:37]
	v_mfma_f32_16x16x32_bf16 v[38:41], v[168:171], v[184:187], v[38:41]
	v_mfma_f32_16x16x32_bf16 v[18:21], v[160:163], v[204:207], v[18:21]
	v_mfma_f32_16x16x32_bf16 v[22:25], v[168:171], v[204:207], v[22:25]
	v_mfma_f32_16x16x32_bf16 v[2:5], v[160:163], v[222:225], v[2:5]
	v_mfma_f32_16x16x32_bf16 v[6:9], v[168:171], v[222:225], v[6:9]
	v_mfma_f32_16x16x32_bf16 v[50:53], v[164:167], v[180:183], v[50:53]
	v_mfma_f32_16x16x32_bf16 v[54:57], v[172:175], v[180:183], v[54:57]
	v_mfma_f32_16x16x32_bf16 v[34:37], v[164:167], v[188:191], v[34:37]
	v_mfma_f32_16x16x32_bf16 v[38:41], v[172:175], v[188:191], v[38:41]
	v_mfma_f32_16x16x32_bf16 v[18:21], v[164:167], v[218:221], v[18:21]
	v_mfma_f32_16x16x32_bf16 v[22:25], v[172:175], v[218:221], v[22:25]
	v_mfma_f32_16x16x32_bf16 v[2:5], v[164:167], v[226:229], v[2:5]
	v_mfma_f32_16x16x32_bf16 v[6:9], v[172:175], v[226:229], v[6:9]
	s_barrier
	s_setprio 0
	s_add_i32 s18, s39, s2
	v_lshl_add_u64 v[192:193], s[22:23], 0, v[0:1]
	s_mov_b32 m0, s18
	ds_read_b128 v[176:179], v143 offset:16384
	ds_read_b128 v[180:183], v143 offset:17408
	ds_read_b128 v[184:187], v143 offset:18432
	ds_read_b128 v[188:191], v143 offset:19456
	ds_read_b128 v[204:207], v143 offset:20480
	ds_read_b128 v[218:221], v143 offset:21504
	ds_read_b128 v[222:225], v143 offset:22528
	ds_read_b128 v[226:229], v143 offset:23552
	global_load_lds_dwordx4 v[192:193], off
	s_add_i32 m0, s18, 0x2000
	s_add_u32 s18, s22, 0x160000
	v_lshl_add_u64 v[200:201], s[22:23], 0, v[136:137]
	s_addc_u32 s19, s23, 0
	s_add_i32 s39, s40, s2
	global_load_lds_dwordx4 v[200:201], off
	v_lshl_add_u64 v[202:203], s[18:19], 0, v[0:1]
	s_mov_b32 m0, s39
	v_lshl_add_u64 v[230:231], s[24:25], 0, v[134:135]
	global_load_lds_dwordx4 v[202:203], off
	v_lshl_add_u64 v[202:203], s[18:19], 0, v[136:137]
	s_add_i32 m0, s39, 0x2000
	s_nop 0
	global_load_lds_dwordx4 v[202:203], off
	v_lshl_add_u64 v[202:203], s[24:25], 0, v[132:133]
	s_mov_b32 m0, s3
	s_nop 0
	global_load_lds_dwordx4 v[202:203], off
	s_mov_b32 m0, s10
	s_nop 0
	global_load_lds_dwordx4 v[230:231], off
	s_waitcnt vmcnt(8)
	s_waitcnt lgkmcnt(0)
	s_setprio 1
	s_barrier
; #define PG8_STAGE(bufoff, gbase, voff) do { _Pragma("unroll") for (int _i = 0; _i < 2; ++_i) \
;         __builtin_amdgcn_global_load_lds((const unsigned*)((const char*)(gbase) + (voff)[_i]), (PG8_LAS unsigned*)(lds + (bufoff) + ldsw + _i * 8192), 16, 0, 0); } while (0)
; #define PG8_LDA(dst, b, h) do { _Pragma("unroll") for (int m = 0; m < 4; ++m) _Pragma("unroll") for (int k = 0; k < 2; ++k) dst[m][k] = *(const PG8_LAS bf16x8*)(lds + PG8_SA(b, h) + aoff + m * 2048 + k * 1024); } while (0)
; #define PG8_LDB(dst, b, h) do { _Pragma("unroll") for (int n = 0; n < 2; ++n) _Pragma("unroll") for (int k = 0; k < 2; ++k) dst[n][k] = *(const PG8_LAS bf16x8*)(lds + PG8_SB(b, h) + boff + n * 2048 + k * 1024); } while (0)
; #define PG8_MMA(ai, bj, At, Bt) do { __builtin_amdgcn_s_setprio(1); _Pragma("unroll") for (int m = 0; m < 4; ++m) _Pragma("unroll") for (int n = 0; n < 2; ++n) _Pragma("unroll") for (int k = 0; k < 2; ++k) \
;         acc[ai][bj][m][n] = __builtin_amdgcn_mfma_f32_16x16x32_bf16(Bt[n][k], At[m][k], acc[ai][bj][m][n], 0, 0, 0); __builtin_amdgcn_s_setprio(0); } while (0)
; #define PG8_WAIT_V(n) asm volatile("s_waitcnt vmcnt(" #n ")" ::: "memory")
; #define PG8_WAIT_L(n) asm volatile("s_waitcnt lgkmcnt(" #n ")" ::: "memory")
; #define PG8_BAR __builtin_amdgcn_s_barrier()
; #define PG8_SCHED __builtin_amdgcn_sched_barrier(0)
; template <class Epi, class Sched, bool ALIGN_EPI = false, bool SP2 = false>
; __device__ __forceinline__ void gemm_phase(PG8_LAS unsigned char* lds, const Gemm g, const Sched& S, const Epi& E) {
;     ...
;             PG8_WAIT_V(8); PG8_WAIT_L(0); PG8_BAR; PG8_MMA(1, 0, At, B0); PG8_MMA(1, 1, At, B1); PG8_BAR; PG8_SCHED;
;             PG8_LDB(B0, 1, 0); PG8_LDB(B1, 1, 1); PG8_SCHED; PG8_LDA(At, 1, 0); PG8_STAGE(PG8_SA(0, 1), a2 + hstep, voffA);
;             PG8_WAIT_V(8); PG8_WAIT_L(0); PG8_BAR; PG8_MMA(0, 0, At, B0); PG8_MMA(0, 1, At, B1); PG8_BAR; PG8_SCHED;
	v_mfma_f32_16x16x32_bf16 v[90:93], v[144:147], v[176:179], v[90:93]
	v_mfma_f32_16x16x32_bf16 v[94:97], v[152:155], v[176:179], v[94:97]
	v_mfma_f32_16x16x32_bf16 v[74:77], v[144:147], v[184:187], v[74:77]
	v_mfma_f32_16x16x32_bf16 v[78:81], v[152:155], v[184:187], v[78:81]
	v_mfma_f32_16x16x32_bf16 v[122:125], v[144:147], v[204:207], v[122:125]
	v_mfma_f32_16x16x32_bf16 v[126:129], v[152:155], v[204:207], v[126:129]
	v_mfma_f32_16x16x32_bf16 v[106:109], v[144:147], v[222:225], v[106:109]
	v_mfma_f32_16x16x32_bf16 v[110:113], v[152:155], v[222:225], v[110:113]
	v_mfma_f32_16x16x32_bf16 v[90:93], v[148:151], v[180:183], v[90:93]
	v_mfma_f32_16x16x32_bf16 v[94:97], v[156:159], v[180:183], v[94:97]
	v_mfma_f32_16x16x32_bf16 v[74:77], v[148:151], v[188:191], v[74:77]
	v_mfma_f32_16x16x32_bf16 v[78:81], v[156:159], v[188:191], v[78:81]
	v_mfma_f32_16x16x32_bf16 v[122:125], v[148:151], v[218:221], v[122:125]
	v_mfma_f32_16x16x32_bf16 v[126:129], v[156:159], v[218:221], v[126:129]
	v_mfma_f32_16x16x32_bf16 v[106:109], v[148:151], v[226:229], v[106:109]
	v_mfma_f32_16x16x32_bf16 v[110:113], v[156:159], v[226:229], v[110:113]
	s_setprio 0
	s_setprio 1
	v_mfma_f32_16x16x32_bf16 v[82:85], v[160:163], v[176:179], v[82:85]
	v_mfma_f32_16x16x32_bf16 v[86:89], v[168:171], v[176:179], v[86:89]
	v_mfma_f32_16x16x32_bf16 v[66:69], v[160:163], v[184:187], v[66:69]
	v_mfma_f32_16x16x32_bf16 v[70:73], v[168:171], v[184:187], v[70:73]
	v_mfma_f32_16x16x32_bf16 v[114:117], v[160:163], v[204:207], v[114:117]
	v_mfma_f32_16x16x32_bf16 v[118:121], v[168:171], v[204:207], v[118:121]
	v_mfma_f32_16x16x32_bf16 v[102:105], v[160:163], v[222:225], v[102:105]
	v_mfma_f32_16x16x32_bf16 v[98:101], v[168:171], v[222:225], v[98:101]
	v_mfma_f32_16x16x32_bf16 v[82:85], v[164:167], v[180:183], v[82:85]
	v_mfma_f32_16x16x32_bf16 v[86:89], v[172:175], v[180:183], v[86:89]
	v_mfma_f32_16x16x32_bf16 v[66:69], v[164:167], v[188:191], v[66:69]
	v_mfma_f32_16x16x32_bf16 v[70:73], v[172:175], v[188:191], v[70:73]
	v_mfma_f32_16x16x32_bf16 v[114:117], v[164:167], v[218:221], v[114:117]
	v_mfma_f32_16x16x32_bf16 v[118:121], v[172:175], v[218:221], v[118:121]
	v_mfma_f32_16x16x32_bf16 v[102:105], v[164:167], v[226:229], v[102:105]
	v_mfma_f32_16x16x32_bf16 v[98:101], v[172:175], v[226:229], v[98:101]
	s_barrier
	s_setprio 0
	s_add_i32 s39, 0, 0x18000
	s_add_i32 s40, 0, 0x1c000
	v_add_u32_e32 v156, s39, v142
	v_add_u32_e32 v172, s40, v142
	ds_read_b128 v[144:147], v156
	ds_read_b128 v[148:151], v156 offset:1024
	ds_read_b128 v[152:155], v156 offset:2048
	ds_read_b128 v[156:159], v156 offset:3072
	ds_read_b128 v[160:163], v172
	ds_read_b128 v[164:167], v172 offset:1024
	ds_read_b128 v[168:171], v172 offset:2048
	ds_read_b128 v[172:175], v172 offset:3072
	s_add_u32 s18, s24, 0x160000
	s_addc_u32 s19, s25, 0
	s_mov_b32 m0, s11
	v_lshl_add_u64 v[232:233], s[18:19], 0, v[132:133]
	ds_read_b128 v[176:179], v143 offset:32768
	ds_read_b128 v[180:183], v143 offset:33792
	ds_read_b128 v[184:187], v143 offset:34816
	ds_read_b128 v[188:191], v143 offset:35840
	ds_read_b128 v[204:207], v143 offset:36864
	ds_read_b128 v[218:221], v143 offset:37888
	ds_read_b128 v[222:225], v143 offset:38912
	ds_read_b128 v[226:229], v143 offset:39936
	global_load_lds_dwordx4 v[232:233], off
	v_lshl_add_u64 v[232:233], s[18:19], 0, v[134:135]
	s_mov_b32 m0, s27
	s_nop 0
	global_load_lds_dwordx4 v[232:233], off
	s_waitcnt vmcnt(8)
	s_waitcnt lgkmcnt(0)
	s_setprio 1
	s_barrier
	v_mfma_f32_16x16x32_bf16 v[58:61], v[144:147], v[176:179], v[58:61]
	v_mfma_f32_16x16x32_bf16 v[62:65], v[152:155], v[176:179], v[62:65]
	v_mfma_f32_16x16x32_bf16 v[42:45], v[144:147], v[184:187], v[42:45]
	v_mfma_f32_16x16x32_bf16 v[46:49], v[152:155], v[184:187], v[46:49]
	v_mfma_f32_16x16x32_bf16 v[26:29], v[144:147], v[204:207], v[26:29]
	v_mfma_f32_16x16x32_bf16 v[30:33], v[152:155], v[204:207], v[30:33]
	v_mfma_f32_16x16x32_bf16 v[10:13], v[144:147], v[222:225], v[10:13]
	v_mfma_f32_16x16x32_bf16 v[14:17], v[152:155], v[222:225], v[14:17]
	v_mfma_f32_16x16x32_bf16 v[58:61], v[148:151], v[180:183], v[58:61]
	v_mfma_f32_16x16x32_bf16 v[62:65], v[156:159], v[180:183], v[62:65]
	v_mfma_f32_16x16x32_bf16 v[42:45], v[148:151], v[188:191], v[42:45]
	v_mfma_f32_16x16x32_bf16 v[46:49], v[156:159], v[188:191], v[46:49]
	v_mfma_f32_16x16x32_bf16 v[26:29], v[148:151], v[218:221], v[26:29]
	v_mfma_f32_16x16x32_bf16 v[30:33], v[156:159], v[218:221], v[30:33]
	v_mfma_f32_16x16x32_bf16 v[10:13], v[148:151], v[226:229], v[10:13]
	v_mfma_f32_16x16x32_bf16 v[14:17], v[156:159], v[226:229], v[14:17]
	s_setprio 0
	s_setprio 1
	v_mfma_f32_16x16x32_bf16 v[50:53], v[160:163], v[176:179], v[50:53]
	v_mfma_f32_16x16x32_bf16 v[54:57], v[168:171], v[176:179], v[54:57]
	v_mfma_f32_16x16x32_bf16 v[34:37], v[160:163], v[184:187], v[34:37]
	v_mfma_f32_16x16x32_bf16 v[38:41], v[168:171], v[184:187], v[38:41]
	v_mfma_f32_16x16x32_bf16 v[18:21], v[160:163], v[204:207], v[18:21]
	v_mfma_f32_16x16x32_bf16 v[22:25], v[168:171], v[204:207], v[22:25]
	v_mfma_f32_16x16x32_bf16 v[2:5], v[160:163], v[222:225], v[2:5]
	v_mfma_f32_16x16x32_bf16 v[6:9], v[168:171], v[222:225], v[6:9]
	v_mfma_f32_16x16x32_bf16 v[50:53], v[164:167], v[180:183], v[50:53]
	v_mfma_f32_16x16x32_bf16 v[54:57], v[172:175], v[180:183], v[54:57]
	v_mfma_f32_16x16x32_bf16 v[34:37], v[164:167], v[188:191], v[34:37]
	v_mfma_f32_16x16x32_bf16 v[38:41], v[172:175], v[188:191], v[38:41]
	v_mfma_f32_16x16x32_bf16 v[18:21], v[164:167], v[218:221], v[18:21]
	v_mfma_f32_16x16x32_bf16 v[22:25], v[172:175], v[218:221], v[22:25]
	v_mfma_f32_16x16x32_bf16 v[2:5], v[164:167], v[226:229], v[2:5]
	v_mfma_f32_16x16x32_bf16 v[6:9], v[172:175], v[226:229], v[6:9]
	s_barrier
; #define PG8_STAGE(bufoff, gbase, voff) do { _Pragma("unroll") for (int _i = 0; _i < 2; ++_i) \
;         __builtin_amdgcn_global_load_lds((const unsigned*)((const char*)(gbase) + (voff)[_i]), (PG8_LAS unsigned*)(lds + (bufoff) + ldsw + _i * 8192), 16, 0, 0); } while (0)
; #define PG8_LDA(dst, b, h) do { _Pragma("unroll") for (int m = 0; m < 4; ++m) _Pragma("unroll") for (int k = 0; k < 2; ++k) dst[m][k] = *(const PG8_LAS bf16x8*)(lds + PG8_SA(b, h) + aoff + m * 2048 + k * 1024); } while (0)
; #define PG8_MMA(ai, bj, At, Bt) do { __builtin_amdgcn_s_setprio(1); _Pragma("unroll") for (int m = 0; m < 4; ++m) _Pragma("unroll") for (int n = 0; n < 2; ++n) _Pragma("unroll") for (int k = 0; k < 2; ++k) \
;         acc[ai][bj][m][n] = __builtin_amdgcn_mfma_f32_16x16x32_bf16(Bt[n][k], At[m][k], acc[ai][bj][m][n], 0, 0, 0); __builtin_amdgcn_s_setprio(0); } while (0)
; #define PG8_WAIT_V(n) asm volatile("s_waitcnt vmcnt(" #n ")" ::: "memory")
; #define PG8_WAIT_L(n) asm volatile("s_waitcnt lgkmcnt(" #n ")" ::: "memory")
; #define PG8_BAR __builtin_amdgcn_s_barrier()
; #define PG8_SCHED __builtin_amdgcn_sched_barrier(0)
; template <class Epi, class Sched, bool ALIGN_EPI = false, bool SP2 = false>
; __device__ __forceinline__ void gemm_phase(PG8_LAS unsigned char* lds, const Gemm g, const Sched& S, const Epi& E) {
;     ...
;         for (int t = 0; t < nt; t += 2) {
;             const bool last = (t == nt - 2);
;             const char* a1 = cA + (size_t)(t + 1) * kstep;
;             const char* a2 = last ? nA : cA + (size_t)(t + 2) * kstep; const char* b2 = last ? nB : cB + (size_t)(t + 2) * kstep;
;     ...
;             PG8_LDA(At, 1, 1); PG8_STAGE(PG8_SB(1, 0), b3, voffB); PG8_STAGE(PG8_SB(1, 1), b3 + hstep, voffB); PG8_STAGE(PG8_SA(1, 0), a3, voffA);
;             PG8_WAIT_V(8); PG8_WAIT_L(0); PG8_BAR; PG8_MMA(1, 0, At, B0); PG8_MMA(1, 1, At, B1); PG8_BAR; PG8_SCHED;
	s_setprio 0
	s_add_i32 s18, s39, s2
	v_lshl_add_u64 v[192:193], v[192:193], 0, s[56:57]
	s_mov_b32 m0, s18
	ds_read_b128 v[176:179], v143 offset:49152
	ds_read_b128 v[180:183], v143 offset:50176
	ds_read_b128 v[184:187], v143 offset:51200
	ds_read_b128 v[188:191], v143 offset:52224
	ds_read_b128 v[204:207], v143 offset:53248
	ds_read_b128 v[218:221], v143 offset:54272
	ds_read_b128 v[222:225], v143 offset:55296
	ds_read_b128 v[226:229], v143 offset:56320
	global_load_lds_dwordx4 v[192:193], off
	s_add_i32 m0, s18, 0x2000
	s_add_u32 s18, s22, 0x160080
	v_lshl_add_u64 v[192:193], v[200:201], 0, s[56:57]
	s_addc_u32 s19, s23, 0
	s_add_i32 s22, s40, s2
	global_load_lds_dwordx4 v[192:193], off
	v_lshl_add_u64 v[192:193], s[18:19], 0, v[0:1]
	s_mov_b32 m0, s22
	s_nop 0
	global_load_lds_dwordx4 v[192:193], off
	v_lshl_add_u64 v[192:193], s[18:19], 0, v[136:137]
	s_add_i32 m0, s22, 0x2000
	s_nop 0
	global_load_lds_dwordx4 v[192:193], off
	v_lshl_add_u64 v[192:193], v[202:203], 0, s[56:57]
	s_mov_b32 m0, s33
	s_nop 0
	global_load_lds_dwordx4 v[192:193], off
	v_lshl_add_u64 v[192:193], v[230:231], 0, s[56:57]
	s_mov_b32 m0, s37
	s_nop 0
	global_load_lds_dwordx4 v[192:193], off
	s_waitcnt vmcnt(8)
	s_waitcnt lgkmcnt(0)
	s_setprio 1
	s_barrier
	v_mfma_f32_16x16x32_bf16 v[90:93], v[144:147], v[176:179], v[90:93]
	v_mfma_f32_16x16x32_bf16 v[94:97], v[152:155], v[176:179], v[94:97]
	v_mfma_f32_16x16x32_bf16 v[74:77], v[144:147], v[184:187], v[74:77]
	v_mfma_f32_16x16x32_bf16 v[78:81], v[152:155], v[184:187], v[78:81]
	v_mfma_f32_16x16x32_bf16 v[122:125], v[144:147], v[204:207], v[122:125]
	v_mfma_f32_16x16x32_bf16 v[126:129], v[152:155], v[204:207], v[126:129]
	v_mfma_f32_16x16x32_bf16 v[106:109], v[144:147], v[222:225], v[106:109]
	v_mfma_f32_16x16x32_bf16 v[110:113], v[152:155], v[222:225], v[110:113]
	v_mfma_f32_16x16x32_bf16 v[90:93], v[148:151], v[180:183], v[90:93]
	v_mfma_f32_16x16x32_bf16 v[94:97], v[156:159], v[180:183], v[94:97]
	v_mfma_f32_16x16x32_bf16 v[74:77], v[148:151], v[188:191], v[74:77]
	v_mfma_f32_16x16x32_bf16 v[78:81], v[156:159], v[188:191], v[78:81]
	v_mfma_f32_16x16x32_bf16 v[122:125], v[148:151], v[218:221], v[122:125]
	v_mfma_f32_16x16x32_bf16 v[126:129], v[156:159], v[218:221], v[126:129]
	v_mfma_f32_16x16x32_bf16 v[106:109], v[148:151], v[226:229], v[106:109]
	v_mfma_f32_16x16x32_bf16 v[110:113], v[156:159], v[226:229], v[110:113]
	s_setprio 0
	s_setprio 1
	v_mfma_f32_16x16x32_bf16 v[82:85], v[160:163], v[176:179], v[82:85]
	v_mfma_f32_16x16x32_bf16 v[86:89], v[168:171], v[176:179], v[86:89]
	v_mfma_f32_16x16x32_bf16 v[66:69], v[160:163], v[184:187], v[66:69]
	v_mfma_f32_16x16x32_bf16 v[70:73], v[168:171], v[184:187], v[70:73]
	v_mfma_f32_16x16x32_bf16 v[114:117], v[160:163], v[204:207], v[114:117]
	v_mfma_f32_16x16x32_bf16 v[118:121], v[168:171], v[204:207], v[118:121]
	v_mfma_f32_16x16x32_bf16 v[102:105], v[160:163], v[222:225], v[102:105]
	v_mfma_f32_16x16x32_bf16 v[98:101], v[168:171], v[222:225], v[98:101]
	v_mfma_f32_16x16x32_bf16 v[82:85], v[164:167], v[180:183], v[82:85]
	v_mfma_f32_16x16x32_bf16 v[86:89], v[172:175], v[180:183], v[86:89]
	v_mfma_f32_16x16x32_bf16 v[66:69], v[164:167], v[188:191], v[66:69]
	v_mfma_f32_16x16x32_bf16 v[70:73], v[172:175], v[188:191], v[70:73]
	v_mfma_f32_16x16x32_bf16 v[114:117], v[164:167], v[218:221], v[114:117]
	v_mfma_f32_16x16x32_bf16 v[118:121], v[172:175], v[218:221], v[118:121]
	v_mfma_f32_16x16x32_bf16 v[102:105], v[164:167], v[226:229], v[102:105]
	v_mfma_f32_16x16x32_bf16 v[98:101], v[172:175], v[226:229], v[98:101]
	s_barrier
	s_setprio 0
	s_add_i32 s38, s38, 2
	s_cmp_gt_u32 s38, 19
	s_mov_b64 s[18:19], s[20:21]
	s_cbranch_scc0 .LBB0_1027
	s_cmpk_lt_u32 s1, 0x100
	s_cbranch_scc0 .LBB0_1030
	s_barrier
